# combo2 = combo1 + batched rstd partial-sum loads in first-tile epilogues (proj, swiglu) + batched V staging loads in memory attention
# speedup vs baseline: 1.0047x; 1.0035x over previous
; __global__ void __launch_bounds__(512, 2) mk_fwd(Args a) {
;     ...
;                     const int w = it & 255, kk = it >> 8, b = w & 63, sl = (w >> 6) + 4 * kk, tok0 = 256 * b;
;                     if (sl < 8) {
;     ...
;                         { const int m = tid >> 1, hf = tid & 1;
;                           const f32x4* kr = (const f32x4*)(MKV + (size_t)(256 * l + m) * 2048 + 1024 * l + 128 * hm + 64 * hf);
;                           const f32x4* gk = (const f32x4*)((const float*)a.in[14] + l * HD + 64 * hf);
;                           f32x4 v[16]; float ss = 0.f;
; #pragma unroll
;                           for (int i = 0; i < 16; ++i) { v[i] = kr[i]; ss += (v[i][0] * v[i][0] + v[i][1] * v[i][1]) + (v[i][2] * v[i][2] + v[i][3] * v[i][3]); }
.LBB0_397:
	s_ashr_i32 s6, s21, 6
	s_and_b32 s22, s21, 63
	s_bfe_u32 s0, s21, 0x20006
	s_and_b32 s1, s6, -4
	s_or_b32 s23, s0, s1
	s_lshl_b32 s24, s22, 8
	s_cmp_gt_i32 s23, 7
	s_mov_b64 s[0:1], -1
	s_cbranch_scc0 .LBB0_406
	s_cmp_gt_u32 s6, 11
	s_cbranch_scc0 .LBB0_402
	v_mov_b32_e32 v75, v232
	s_lshl_b32 s1, s23, 7
	v_ashrrev_i32_e32 v64, 1, v75
	v_add_u32_e32 v0, s20, v64
	v_ashrrev_i32_e32 v1, 31, v0
	v_lshlrev_b64 v[0:1], 13, v[0:1]
	v_and_b32_e32 v77, 1, v75
	v_lshl_add_u64 v[0:1], s[18:19], 0, v[0:1]
	s_add_i32 s74, s1, 0xfffffa00
	v_lshl_add_u64 v[0:1], s[74:75], 2, v[0:1]
	v_lshlrev_b32_e32 v128, 8, v77
	v_lshl_add_u64 v[72:73], v[0:1], 0, v[128:129]
	flat_load_dwordx4 v[44:47], v[72:73]
	flat_load_dwordx4 v[56:59], v[72:73] offset:16
	flat_load_dwordx4 v[52:55], v[72:73] offset:32
	flat_load_dwordx4 v[60:63], v[72:73] offset:48
	flat_load_dwordx4 v[24:27], v[72:73] offset:64
	flat_load_dwordx4 v[28:31], v[72:73] offset:80
	flat_load_dwordx4 v[36:39], v[72:73] offset:96
	flat_load_dwordx4 v[48:51], v[72:73] offset:112
	flat_load_dwordx4 v[16:19], v[72:73] offset:128
	flat_load_dwordx4 v[20:23], v[72:73] offset:144
	flat_load_dwordx4 v[32:35], v[72:73] offset:160
	v_mul_lo_u32 v64, v64, s86
	v_readfirstlane_b32 s0, v75
	v_readlane_b32 s2, v254, 28
	v_and_b32_e32 v165, 31, v75
	v_mov_b32_e32 v166, 0
	s_mov_b32 s14, s25
	s_mov_b32 s25, 0
	s_waitcnt vmcnt(0) lgkmcnt(0)
	v_pk_mul_f32 v[0:1], v[46:47], v[46:47]
	v_pk_mul_f32 v[2:3], v[44:45], v[44:45]
	s_nop 0
	v_pk_mov_b32 v[4:5], v[2:3], v[0:1] op_sel:[1,0]
	v_mov_b32_e32 v3, v1
	v_pk_add_f32 v[0:1], v[4:5], v[2:3]
	v_pk_mul_f32 v[2:3], v[58:59], v[58:59]
	v_pk_mul_f32 v[4:5], v[56:57], v[56:57]
	v_pk_add_f32 v[0:1], v[0:1], v[0:1] op_sel:[0,1] op_sel_hi:[1,0]
	v_pk_mov_b32 v[6:7], v[4:5], v[2:3] op_sel:[1,0]
	v_mov_b32_e32 v5, v3
	v_pk_add_f32 v[2:3], v[6:7], v[4:5]
	v_mul_f32_e32 v4, v60, v60
	v_mul_f32_e32 v5, v61, v61
	v_pk_add_f32 v[2:3], v[2:3], v[2:3] op_sel:[0,1] op_sel_hi:[1,0]
	v_mov_b32_e32 v1, v4
	v_mov_b32_e32 v3, v5
	v_pk_add_f32 v[0:1], v[0:1], v[2:3]
	v_mul_f32_e32 v2, v53, v53
	v_mul_f32_e32 v4, v55, v55
	v_mul_f32_e32 v6, v62, v62
	v_mul_f32_e32 v7, v63, v63
	v_pk_fma_f32 v[2:3], v[52:53], v[52:53], v[2:3] op_sel_hi:[1,1,0]
	v_pk_fma_f32 v[4:5], v[54:55], v[54:55], v[4:5] op_sel_hi:[1,1,0]
	v_mov_b32_e32 v3, v6
	v_mov_b32_e32 v5, v7
	v_pk_add_f32 v[2:3], v[2:3], v[4:5]
	v_pk_mul_f32 v[4:5], v[24:25], v[24:25]
	v_pk_add_f32 v[0:1], v[0:1], v[2:3]
	v_pk_mul_f32 v[2:3], v[26:27], v[26:27]
	v_pk_add_f32 v[0:1], v[0:1], v[0:1] op_sel:[0,1] op_sel_hi:[1,0]
	v_pk_mov_b32 v[6:7], v[4:5], v[2:3] op_sel:[1,0]
	v_mov_b32_e32 v5, v3
	v_pk_add_f32 v[2:3], v[6:7], v[4:5]
	v_mul_f32_e32 v4, v36, v36
	v_mul_f32_e32 v5, v37, v37
	v_pk_add_f32 v[2:3], v[2:3], v[2:3] op_sel:[0,1] op_sel_hi:[1,0]
	v_mov_b32_e32 v1, v4
	v_mov_b32_e32 v3, v5
	v_pk_add_f32 v[0:1], v[0:1], v[2:3]
	v_mul_f32_e32 v2, v29, v29
	v_mul_f32_e32 v4, v31, v31
	v_mul_f32_e32 v6, v38, v38
	v_mul_f32_e32 v7, v39, v39
	v_pk_fma_f32 v[2:3], v[28:29], v[28:29], v[2:3] op_sel_hi:[1,1,0]
	v_pk_fma_f32 v[4:5], v[30:31], v[30:31], v[4:5] op_sel_hi:[1,1,0]
	v_mov_b32_e32 v3, v6
	v_mov_b32_e32 v5, v7
	v_pk_add_f32 v[2:3], v[2:3], v[4:5]
	v_pk_mul_f32 v[4:5], v[48:49], v[48:49]
	v_pk_add_f32 v[0:1], v[0:1], v[2:3]
	v_pk_mul_f32 v[2:3], v[50:51], v[50:51]
	v_pk_add_f32 v[0:1], v[0:1], v[0:1] op_sel:[0,1] op_sel_hi:[1,0]
	v_pk_mov_b32 v[6:7], v[4:5], v[2:3] op_sel:[1,0]
	v_mov_b32_e32 v5, v3
	v_pk_add_f32 v[2:3], v[6:7], v[4:5]
	v_mul_f32_e32 v4, v20, v20
	v_mul_f32_e32 v5, v21, v21
	v_pk_add_f32 v[2:3], v[2:3], v[2:3] op_sel:[0,1] op_sel_hi:[1,0]
	v_mov_b32_e32 v1, v4
	v_mov_b32_e32 v3, v5
	v_pk_add_f32 v[0:1], v[0:1], v[2:3]
	v_mul_f32_e32 v2, v17, v17
	v_mul_f32_e32 v4, v19, v19
	v_mul_f32_e32 v6, v22, v22
	v_mul_f32_e32 v7, v23, v23
	v_pk_fma_f32 v[2:3], v[16:17], v[16:17], v[2:3] op_sel_hi:[1,1,0]
	v_pk_fma_f32 v[4:5], v[18:19], v[18:19], v[4:5] op_sel_hi:[1,1,0]
	v_mov_b32_e32 v3, v6
	v_mov_b32_e32 v5, v7
	v_pk_add_f32 v[2:3], v[2:3], v[4:5]
	s_nop 0
	v_pk_add_f32 v[4:5], v[0:1], v[2:3]
	v_pk_mul_f32 v[0:1], v[34:35], v[34:35]
	v_pk_mul_f32 v[2:3], v[32:33], v[32:33]
	v_pk_add_f32 v[4:5], v[4:5], v[4:5] op_sel:[0,1] op_sel_hi:[1,0]
	v_pk_mov_b32 v[6:7], v[2:3], v[0:1] op_sel:[1,0]
	v_mov_b32_e32 v3, v1
	v_pk_add_f32 v[6:7], v[6:7], v[2:3]
	flat_load_dwordx4 v[40:43], v[72:73] offset:176
	flat_load_dwordx4 v[0:3], v[72:73] offset:192
	v_pk_add_f32 v[6:7], v[6:7], v[6:7] op_sel:[0,1] op_sel_hi:[1,0]
	s_waitcnt vmcnt(0) lgkmcnt(0)
	v_mul_f32_e32 v8, v0, v0
	v_mul_f32_e32 v9, v1, v1
	v_mov_b32_e32 v5, v8
	v_mov_b32_e32 v7, v9
	v_pk_add_f32 v[4:5], v[4:5], v[6:7]
	v_mul_f32_e32 v6, v41, v41
	v_mul_f32_e32 v8, v43, v43
	v_mul_f32_e32 v10, v2, v2
	v_mul_f32_e32 v11, v3, v3
	v_pk_fma_f32 v[6:7], v[40:41], v[40:41], v[6:7] op_sel_hi:[1,1,0]
	v_pk_fma_f32 v[8:9], v[42:43], v[42:43], v[8:9] op_sel_hi:[1,1,0]
	v_mov_b32_e32 v7, v10
	v_mov_b32_e32 v9, v11
	v_pk_add_f32 v[6:7], v[6:7], v[8:9]
	s_nop 0
	v_pk_add_f32 v[66:67], v[4:5], v[6:7]
	flat_load_dwordx4 v[4:7], v[72:73] offset:208
	v_pk_add_f32 v[66:67], v[66:67], v[66:67] op_sel:[0,1] op_sel_hi:[1,0]
	s_waitcnt vmcnt(0) lgkmcnt(0)
	v_pk_mul_f32 v[8:9], v[6:7], v[6:7]
	v_pk_mul_f32 v[10:11], v[4:5], v[4:5]
	s_nop 0
	v_pk_mov_b32 v[12:13], v[10:11], v[8:9] op_sel:[1,0]
	v_mov_b32_e32 v11, v9
	v_pk_add_f32 v[68:69], v[12:13], v[10:11]
	flat_load_dwordx4 v[12:15], v[72:73] offset:224
	flat_load_dwordx4 v[8:11], v[72:73] offset:240
	v_pk_add_f32 v[68:69], v[68:69], v[68:69] op_sel:[0,1] op_sel_hi:[1,0]
	s_waitcnt vmcnt(0) lgkmcnt(0)
; #define LAS __attribute__((address_space(3)))
; __device__ __forceinline__ unsigned cvtpk(float lo, float hi) { f32x2 v = {lo, hi}; bf16x2_t b = __builtin_convertvector(v, bf16x2_t); return __builtin_bit_cast(unsigned, b); }
; __global__ void __launch_bounds__(512, 2) mk_fwd(Args a) {
;     ...
;                           ss += __shfl_xor(ss, 1);
;                           const float rstd = 1.0f / sqrtf(ss * (1.0f / 128.0f) + 1e-6f);
; #pragma unroll
;                           for (int i = 0; i < 8; ++i) { const f32x4 g0 = gk[2 * i], g1 = gk[2 * i + 1]; const f32x4 p0 = v[2 * i] * rstd * g0, p1 = v[2 * i + 1] * rstd * g1;
;                               u32x4 o; o.x = cvtpk(p0[0], p0[1]); o.y = cvtpk(p0[2], p0[3]); o.z = cvtpk(p1[0], p1[1]); o.w = cvtpk(p1[2], p1[3]);
;                               *(LAS u32x4*)(lds + LDS_KS + m * KS_STRIDE + 128 * hf + 16 * i) = o; }
	v_mul_f32_e32 v65, v8, v8
	v_mul_f32_e32 v70, v9, v9
	v_mov_b32_e32 v67, v65
	v_mov_b32_e32 v69, v70
	v_pk_add_f32 v[66:67], v[66:67], v[68:69]
	v_mul_f32_e32 v68, v13, v13
	v_mul_f32_e32 v71, v10, v10
	v_pk_fma_f32 v[68:69], v[12:13], v[12:13], v[68:69] op_sel_hi:[1,1,0]
	v_mul_f32_e32 v70, v15, v15
	v_mul_f32_e32 v74, v11, v11
	v_mov_b32_e32 v69, v71
	v_pk_fma_f32 v[70:71], v[14:15], v[14:15], v[70:71] op_sel_hi:[1,1,0]
	s_nop 0
	v_mov_b32_e32 v71, v74
	v_pk_add_f32 v[68:69], v[68:69], v[70:71]
	s_nop 0
	v_pk_add_f32 v[66:67], v[66:67], v[68:69]
	s_nop 0
	v_add_f32_e32 v65, v66, v67
	v_and_b32_e32 v67, 64, v237
	v_xor_b32_e32 v66, 1, v237
	v_add_u32_e32 v76, 64, v67
	v_cmp_lt_i32_e32 vcc, v66, v76
	s_nop 1
	v_cndmask_b32_e32 v66, v237, v66, vcc
	v_lshlrev_b32_e32 v66, 2, v66
	ds_bpermute_b32 v66, v66, v65
	s_waitcnt lgkmcnt(0)
	v_add_f32_e32 v65, v65, v66
	v_fmamk_f32 v65, v65, 0x3c000000, v234
	v_cmp_gt_f32_e32 vcc, s33, v65
	v_mul_f32_e32 v66, 0x4f800000, v65
	s_nop 0
	v_cndmask_b32_e32 v65, v65, v66, vcc
	v_sqrt_f32_e32 v66, v65
	s_nop 0
	v_add_u32_e32 v67, -1, v66
	v_fma_f32 v68, -v67, v66, v65
	v_cmp_ge_f32_e64 s[6:7], 0, v68
	v_add_u32_e32 v68, 1, v66
	s_nop 0
	v_cndmask_b32_e64 v67, v66, v67, s[6:7]
	v_fma_f32 v66, -v68, v66, v65
	v_cmp_lt_f32_e64 s[6:7], 0, v66
	s_nop 1
	v_cndmask_b32_e64 v66, v67, v68, s[6:7]
	v_mul_f32_e32 v67, 0x37800000, v66
	v_cndmask_b32_e32 v66, v66, v67, vcc
	v_cmp_class_f32_e32 vcc, v65, v235
	s_nop 1
	v_cndmask_b32_e32 v65, v66, v65, vcc
	v_div_scale_f32 v66, s[6:7], v65, v65, 1.0
	v_rcp_f32_e32 v67, v66
	s_nop 0
	v_fma_f32 v68, -v66, v67, 1.0
	v_fmac_f32_e32 v67, v68, v67
	v_div_scale_f32 v68, vcc, 1.0, v65, 1.0
	v_mul_f32_e32 v69, v68, v67
	v_fma_f32 v70, -v66, v69, v68
	v_fmac_f32_e32 v69, v70, v67
	v_fma_f32 v66, -v66, v69, v68
	v_div_fmas_f32 v66, v66, v67, v69
	v_div_fixup_f32 v74, v66, v65, 1.0
	v_lshlrev_b32_e32 v65, 7, v77
	v_add3_u32 v78, 0, v64, v65
	global_load_dwordx4 v[64:67], v128, s[30:31] offset:48
	global_load_dwordx4 v[68:71], v128, s[30:31] offset:32
	global_load_dwordx4 v[80:83], v128, s[30:31] offset:16
	global_load_dwordx4 v[84:87], v128, s[30:31]
	v_pk_mul_f32 v[44:45], v[74:75], v[44:45] op_sel_hi:[0,1]
	v_pk_mul_f32 v[46:47], v[74:75], v[46:47] op_sel_hi:[0,1]
	v_pk_mul_f32 v[56:57], v[74:75], v[56:57] op_sel_hi:[0,1]
	v_pk_mul_f32 v[58:59], v[74:75], v[58:59] op_sel_hi:[0,1]
	v_pk_mul_f32 v[24:25], v[74:75], v[24:25] op_sel_hi:[0,1]
	v_pk_mul_f32 v[26:27], v[74:75], v[26:27] op_sel_hi:[0,1]
	v_pk_mul_f32 v[28:29], v[74:75], v[28:29] op_sel_hi:[0,1]
	v_pk_mul_f32 v[30:31], v[74:75], v[30:31] op_sel_hi:[0,1]
	v_pk_mul_f32 v[16:17], v[74:75], v[16:17] op_sel_hi:[0,1]
	v_pk_mul_f32 v[18:19], v[74:75], v[18:19] op_sel_hi:[0,1]
	v_pk_mul_f32 v[20:21], v[74:75], v[20:21] op_sel_hi:[0,1]
	v_pk_mul_f32 v[22:23], v[74:75], v[22:23] op_sel_hi:[0,1]
	v_pk_mul_f32 v[0:1], v[74:75], v[0:1] op_sel_hi:[0,1]
	v_pk_mul_f32 v[2:3], v[74:75], v[2:3] op_sel_hi:[0,1]
	v_pk_mul_f32 v[4:5], v[74:75], v[4:5] op_sel_hi:[0,1]
	v_pk_mul_f32 v[6:7], v[74:75], v[6:7] op_sel_hi:[0,1]
	s_waitcnt vmcnt(1)
	v_pk_mul_f32 v[58:59], v[82:83], v[58:59]
	s_waitcnt vmcnt(0)
	v_pk_mul_f32 v[46:47], v[86:87], v[46:47]
	v_pk_mul_f32 v[44:45], v[84:85], v[44:45]
	v_pk_mul_f32 v[56:57], v[80:81], v[56:57]
	v_cvt_pk_bf16_f32 v44, v44, v45
	v_cvt_pk_bf16_f32 v45, v46, v47
	v_cvt_pk_bf16_f32 v46, v56, v57
	v_cvt_pk_bf16_f32 v47, v58, v59
	ds_write_b128 v78, v[44:47]
	v_pk_mul_f32 v[44:45], v[74:75], v[52:53] op_sel_hi:[0,1]
	v_pk_mul_f32 v[46:47], v[74:75], v[54:55] op_sel_hi:[0,1]
	v_pk_mul_f32 v[52:53], v[74:75], v[60:61] op_sel_hi:[0,1]
	v_pk_mul_f32 v[54:55], v[74:75], v[62:63] op_sel_hi:[0,1]
	v_pk_mul_f32 v[46:47], v[70:71], v[46:47]
	v_pk_mul_f32 v[44:45], v[68:69], v[44:45]
	v_pk_mul_f32 v[54:55], v[66:67], v[54:55]
	v_pk_mul_f32 v[52:53], v[64:65], v[52:53]
	v_cvt_pk_bf16_f32 v44, v44, v45
	v_cvt_pk_bf16_f32 v45, v46, v47
	v_cvt_pk_bf16_f32 v46, v52, v53
	v_cvt_pk_bf16_f32 v47, v54, v55
	ds_write_b128 v78, v[44:47] offset:16
	global_load_dwordx4 v[44:47], v128, s[30:31] offset:112
	global_load_dwordx4 v[52:55], v128, s[30:31] offset:96
	global_load_dwordx4 v[56:59], v128, s[30:31] offset:80
	global_load_dwordx4 v[60:63], v128, s[30:31] offset:64
	s_waitcnt vmcnt(1)
	v_pk_mul_f32 v[30:31], v[58:59], v[30:31]
	s_waitcnt vmcnt(0)
	v_pk_mul_f32 v[26:27], v[62:63], v[26:27]
	v_pk_mul_f32 v[24:25], v[60:61], v[24:25]
	v_pk_mul_f32 v[28:29], v[56:57], v[28:29]
	v_cvt_pk_bf16_f32 v24, v24, v25
	v_cvt_pk_bf16_f32 v25, v26, v27
	v_cvt_pk_bf16_f32 v26, v28, v29
	v_cvt_pk_bf16_f32 v27, v30, v31
	ds_write_b128 v78, v[24:27] offset:32
	v_pk_mul_f32 v[24:25], v[74:75], v[36:37] op_sel_hi:[0,1]
	v_pk_mul_f32 v[26:27], v[74:75], v[38:39] op_sel_hi:[0,1]
	v_pk_mul_f32 v[28:29], v[74:75], v[48:49] op_sel_hi:[0,1]
	v_pk_mul_f32 v[30:31], v[74:75], v[50:51] op_sel_hi:[0,1]
	v_pk_mul_f32 v[26:27], v[54:55], v[26:27]
	v_pk_mul_f32 v[24:25], v[52:53], v[24:25]
	v_pk_mul_f32 v[30:31], v[46:47], v[30:31]
	v_pk_mul_f32 v[28:29], v[44:45], v[28:29]
	v_cvt_pk_bf16_f32 v24, v24, v25
	v_cvt_pk_bf16_f32 v25, v26, v27
	v_cvt_pk_bf16_f32 v26, v28, v29
	v_cvt_pk_bf16_f32 v27, v30, v31
	ds_write_b128 v78, v[24:27] offset:48
	global_load_dwordx4 v[24:27], v128, s[30:31] offset:176
	global_load_dwordx4 v[28:31], v128, s[30:31] offset:160
	global_load_dwordx4 v[36:39], v128, s[30:31] offset:144
	global_load_dwordx4 v[44:47], v128, s[30:31] offset:128
	s_waitcnt vmcnt(1)
	v_pk_mul_f32 v[22:23], v[38:39], v[22:23]
	s_waitcnt vmcnt(0)
; #define LAS __attribute__((address_space(3)))
; __device__ __forceinline__ unsigned cvtpk(float lo, float hi) { f32x2 v = {lo, hi}; bf16x2_t b = __builtin_convertvector(v, bf16x2_t); return __builtin_bit_cast(unsigned, b); }
; __global__ void __launch_bounds__(512, 2) mk_fwd(Args a) {
;     ...
;                           for (int i = 0; i < 8; ++i) { const f32x4 g0 = gk[2 * i], g1 = gk[2 * i + 1]; const f32x4 p0 = v[2 * i] * rstd * g0, p1 = v[2 * i + 1] * rstd * g1;
;                               u32x4 o; o.x = cvtpk(p0[0], p0[1]); o.y = cvtpk(p0[2], p0[3]); o.z = cvtpk(p1[0], p1[1]); o.w = cvtpk(p1[2], p1[3]);
;                               *(LAS u32x4*)(lds + LDS_KS + m * KS_STRIDE + 128 * hf + 16 * i) = o; }
;                           const f32x4* vr = kr + 128;
; #pragma unroll
;                           for (int i = 0; i < 16; ++i) { const f32x4 vv = vr[i];
; #pragma unroll
;                               for (int e = 0; e < 4; ++e) *(LAS bf16_t*)(lds + LDS_VT + (64 * hf + 4 * i + e) * VT_STRIDE + 2 * m) = (bf16_t)(cvtpk(vv[e], 0.f) & 0xffffu); }
	v_pk_mul_f32 v[18:19], v[46:47], v[18:19]
	v_pk_mul_f32 v[16:17], v[44:45], v[16:17]
	v_pk_mul_f32 v[20:21], v[36:37], v[20:21]
	v_cvt_pk_bf16_f32 v16, v16, v17
	v_cvt_pk_bf16_f32 v17, v18, v19
	v_cvt_pk_bf16_f32 v18, v20, v21
	v_cvt_pk_bf16_f32 v19, v22, v23
	ds_write_b128 v78, v[16:19] offset:64
	v_pk_mul_f32 v[16:17], v[74:75], v[32:33] op_sel_hi:[0,1]
	v_pk_mul_f32 v[18:19], v[74:75], v[34:35] op_sel_hi:[0,1]
	v_pk_mul_f32 v[20:21], v[74:75], v[40:41] op_sel_hi:[0,1]
	v_pk_mul_f32 v[22:23], v[74:75], v[42:43] op_sel_hi:[0,1]
	v_pk_mul_f32 v[18:19], v[30:31], v[18:19]
	v_pk_mul_f32 v[16:17], v[28:29], v[16:17]
	v_pk_mul_f32 v[22:23], v[26:27], v[22:23]
	v_pk_mul_f32 v[20:21], v[24:25], v[20:21]
	v_cvt_pk_bf16_f32 v16, v16, v17
	v_cvt_pk_bf16_f32 v17, v18, v19
	v_cvt_pk_bf16_f32 v18, v20, v21
	v_cvt_pk_bf16_f32 v19, v22, v23
	ds_write_b128 v78, v[16:19] offset:80
	global_load_dwordx4 v[16:19], v128, s[30:31] offset:240
	global_load_dwordx4 v[20:23], v128, s[30:31] offset:224
	global_load_dwordx4 v[24:27], v128, s[30:31] offset:208
	global_load_dwordx4 v[28:31], v128, s[30:31] offset:192
	s_waitcnt vmcnt(1)
	v_pk_mul_f32 v[6:7], v[26:27], v[6:7]
	s_waitcnt vmcnt(0)
	v_pk_mul_f32 v[2:3], v[30:31], v[2:3]
	v_pk_mul_f32 v[0:1], v[28:29], v[0:1]
	v_pk_mul_f32 v[4:5], v[24:25], v[4:5]
	v_cvt_pk_bf16_f32 v0, v0, v1
	v_cvt_pk_bf16_f32 v1, v2, v3
	v_cvt_pk_bf16_f32 v2, v4, v5
	v_cvt_pk_bf16_f32 v3, v6, v7
	ds_write_b128 v78, v[0:3] offset:96
	v_pk_mul_f32 v[0:1], v[74:75], v[12:13] op_sel_hi:[0,1]
	v_pk_mul_f32 v[2:3], v[74:75], v[14:15] op_sel_hi:[0,1]
	v_pk_mul_f32 v[4:5], v[74:75], v[8:9] op_sel_hi:[0,1]
	v_pk_mul_f32 v[6:7], v[74:75], v[10:11] op_sel_hi:[0,1]
	v_pk_mul_f32 v[2:3], v[22:23], v[2:3]
	v_pk_mul_f32 v[0:1], v[20:21], v[0:1]
	v_pk_mul_f32 v[6:7], v[18:19], v[6:7]
	v_pk_mul_f32 v[4:5], v[16:17], v[4:5]
	v_cvt_pk_bf16_f32 v0, v0, v1
	v_cvt_pk_bf16_f32 v1, v2, v3
	v_cvt_pk_bf16_f32 v2, v4, v5
	v_cvt_pk_bf16_f32 v3, v6, v7
	ds_write_b128 v78, v[0:3] offset:112
	v_and_b32_e32 v4, -2, v75
	v_mul_u32_u24_e32 v5, 0x8400, v77
	v_add3_u32 v4, s2, v4, v5
	global_load_dwordx4 v[0:3], v[72:73], off offset:2048
	global_load_dwordx4 v[8:11], v[72:73], off offset:2064
	global_load_dwordx4 v[12:15], v[72:73], off offset:2080
	global_load_dwordx4 v[16:19], v[72:73], off offset:2096
	global_load_dwordx4 v[20:23], v[72:73], off offset:2112
	global_load_dwordx4 v[24:27], v[72:73], off offset:2128
	global_load_dwordx4 v[28:31], v[72:73], off offset:2144
	global_load_dwordx4 v[32:35], v[72:73], off offset:2160
	global_load_dwordx4 v[36:39], v[72:73], off offset:2176
	global_load_dwordx4 v[40:43], v[72:73], off offset:2192
	global_load_dwordx4 v[44:47], v[72:73], off offset:2208
	global_load_dwordx4 v[48:51], v[72:73], off offset:2224
	global_load_dwordx4 v[52:55], v[72:73], off offset:2240
	global_load_dwordx4 v[56:59], v[72:73], off offset:2256
	global_load_dwordx4 v[60:63], v[72:73], off offset:2272
	global_load_dwordx4 v[64:67], v[72:73], off offset:2288
	s_waitcnt vmcnt(0) lgkmcnt(0)
	v_cvt_pk_bf16_f32 v0, v0, s0
	ds_write_b16 v4, v0
	v_cvt_pk_bf16_f32 v1, v1, s0
	ds_write_b16 v4, v1 offset:528
	v_cvt_pk_bf16_f32 v2, v2, s0
	ds_write_b16 v4, v2 offset:1056
	v_cvt_pk_bf16_f32 v3, v3, s0
	ds_write_b16 v4, v3 offset:1584
	v_cvt_pk_bf16_f32 v8, v8, s0
	ds_write_b16 v4, v8 offset:2112
	v_cvt_pk_bf16_f32 v9, v9, s0
	ds_write_b16 v4, v9 offset:2640
	v_cvt_pk_bf16_f32 v10, v10, s0
	ds_write_b16 v4, v10 offset:3168
	v_cvt_pk_bf16_f32 v11, v11, s0
	ds_write_b16 v4, v11 offset:3696
	v_cvt_pk_bf16_f32 v12, v12, s0
	ds_write_b16 v4, v12 offset:4224
	v_cvt_pk_bf16_f32 v13, v13, s0
	ds_write_b16 v4, v13 offset:4752
	v_cvt_pk_bf16_f32 v14, v14, s0
	ds_write_b16 v4, v14 offset:5280
	v_cvt_pk_bf16_f32 v15, v15, s0
	ds_write_b16 v4, v15 offset:5808
	v_cvt_pk_bf16_f32 v16, v16, s0
	ds_write_b16 v4, v16 offset:6336
	v_cvt_pk_bf16_f32 v17, v17, s0
	ds_write_b16 v4, v17 offset:6864
	v_cvt_pk_bf16_f32 v18, v18, s0
	ds_write_b16 v4, v18 offset:7392
	v_cvt_pk_bf16_f32 v19, v19, s0
	ds_write_b16 v4, v19 offset:7920
	v_cvt_pk_bf16_f32 v20, v20, s0
	ds_write_b16 v4, v20 offset:8448
	v_cvt_pk_bf16_f32 v21, v21, s0
	ds_write_b16 v4, v21 offset:8976
	v_cvt_pk_bf16_f32 v22, v22, s0
	ds_write_b16 v4, v22 offset:9504
	v_cvt_pk_bf16_f32 v23, v23, s0
	ds_write_b16 v4, v23 offset:10032
	v_cvt_pk_bf16_f32 v24, v24, s0
	ds_write_b16 v4, v24 offset:10560
	v_cvt_pk_bf16_f32 v25, v25, s0
	ds_write_b16 v4, v25 offset:11088
	v_cvt_pk_bf16_f32 v26, v26, s0
	ds_write_b16 v4, v26 offset:11616
	v_cvt_pk_bf16_f32 v27, v27, s0
	ds_write_b16 v4, v27 offset:12144
	v_cvt_pk_bf16_f32 v28, v28, s0
	ds_write_b16 v4, v28 offset:12672
	v_cvt_pk_bf16_f32 v29, v29, s0
	ds_write_b16 v4, v29 offset:13200
	v_cvt_pk_bf16_f32 v30, v30, s0
	ds_write_b16 v4, v30 offset:13728
	v_cvt_pk_bf16_f32 v31, v31, s0
	ds_write_b16 v4, v31 offset:14256
	v_cvt_pk_bf16_f32 v32, v32, s0
	ds_write_b16 v4, v32 offset:14784
	v_cvt_pk_bf16_f32 v33, v33, s0
	ds_write_b16 v4, v33 offset:15312
	v_cvt_pk_bf16_f32 v34, v34, s0
	ds_write_b16 v4, v34 offset:15840
	v_cvt_pk_bf16_f32 v35, v35, s0
	ds_write_b16 v4, v35 offset:16368
	v_cvt_pk_bf16_f32 v36, v36, s0
	ds_write_b16 v4, v36 offset:16896
	v_cvt_pk_bf16_f32 v37, v37, s0
	ds_write_b16 v4, v37 offset:17424
	v_cvt_pk_bf16_f32 v38, v38, s0
	ds_write_b16 v4, v38 offset:17952
	v_cvt_pk_bf16_f32 v39, v39, s0
	ds_write_b16 v4, v39 offset:18480
	v_cvt_pk_bf16_f32 v40, v40, s0
	ds_write_b16 v4, v40 offset:19008
	v_cvt_pk_bf16_f32 v41, v41, s0
	ds_write_b16 v4, v41 offset:19536
	v_cvt_pk_bf16_f32 v42, v42, s0
	ds_write_b16 v4, v42 offset:20064
	v_cvt_pk_bf16_f32 v43, v43, s0
; #define LAS __attribute__((address_space(3)))
; __device__ __forceinline__ unsigned cvtpk(float lo, float hi) { f32x2 v = {lo, hi}; bf16x2_t b = __builtin_convertvector(v, bf16x2_t); return __builtin_bit_cast(unsigned, b); }
; __device__ __forceinline__ float bflo(unsigned w) { return __uint_as_float(w << 16); }
; __device__ __forceinline__ float bfhi(unsigned w) { return __uint_as_float(w & 0xffff0000u); }
; __global__ void __launch_bounds__(512, 2) mk_fwd(Args a) {
;     ...
;                               for (int e = 0; e < 4; ++e) *(LAS bf16_t*)(lds + LDS_VT + (64 * hf + 4 * i + e) * VT_STRIDE + 2 * m) = (bf16_t)(cvtpk(vv[e], 0.f) & 0xffffu); }
;                         }
;                         __syncthreads();
;                         const int tok = tok0 + 32 * wave + r32;
;                         const bf16_t* qrow = PROJ + (size_t)tok * INW + 4608 + 128 * hm + 8 * hi;
;                         const float* gq = (const float*)a.in[13] + l * HD + 8 * hi;
;                         u32x4 qr[8]; float ss = 0.f;
; #pragma unroll
;                         for (int d0 = 0; d0 < 8; ++d0) { qr[d0] = *(const u32x4*)(qrow + 16 * d0);
; #pragma unroll
;                             for (int e = 0; e < 4; ++e) { const float lo = bflo(qr[d0][e]), hh = bfhi(qr[d0][e]); ss += lo * lo + hh * hh; } }
;                         ss += __shfl_xor(ss, 32);
;                         const float rstd = 1.0f / sqrtf(ss * (1.0f / 128.0f) + 1e-6f);
;                         bf16x8 qf[8];
; #pragma unroll
;                         for (int d0 = 0; d0 < 8; ++d0) { u32x4 o;
; #pragma unroll
;                             for (int e = 0; e < 4; ++e) o[e] = cvtpk(bflo(qr[d0][e]) * rstd * gq[16 * d0 + 2 * e], bfhi(qr[d0][e]) * rstd * gq[16 * d0 + 2 * e + 1]);
	ds_write_b16 v4, v43 offset:20592
	v_cvt_pk_bf16_f32 v44, v44, s0
	ds_write_b16 v4, v44 offset:21120
	v_cvt_pk_bf16_f32 v45, v45, s0
	ds_write_b16 v4, v45 offset:21648
	v_cvt_pk_bf16_f32 v46, v46, s0
	ds_write_b16 v4, v46 offset:22176
	v_cvt_pk_bf16_f32 v47, v47, s0
	ds_write_b16 v4, v47 offset:22704
	v_cvt_pk_bf16_f32 v48, v48, s0
	ds_write_b16 v4, v48 offset:23232
	v_cvt_pk_bf16_f32 v49, v49, s0
	ds_write_b16 v4, v49 offset:23760
	v_cvt_pk_bf16_f32 v50, v50, s0
	ds_write_b16 v4, v50 offset:24288
	v_cvt_pk_bf16_f32 v51, v51, s0
	ds_write_b16 v4, v51 offset:24816
	v_cvt_pk_bf16_f32 v52, v52, s0
	ds_write_b16 v4, v52 offset:25344
	v_cvt_pk_bf16_f32 v53, v53, s0
	ds_write_b16 v4, v53 offset:25872
	v_cvt_pk_bf16_f32 v54, v54, s0
	ds_write_b16 v4, v54 offset:26400
	v_cvt_pk_bf16_f32 v55, v55, s0
	ds_write_b16 v4, v55 offset:26928
	v_cvt_pk_bf16_f32 v56, v56, s0
	ds_write_b16 v4, v56 offset:27456
	v_cvt_pk_bf16_f32 v57, v57, s0
	ds_write_b16 v4, v57 offset:27984
	v_cvt_pk_bf16_f32 v58, v58, s0
	ds_write_b16 v4, v58 offset:28512
	v_cvt_pk_bf16_f32 v59, v59, s0
	ds_write_b16 v4, v59 offset:29040
	v_cvt_pk_bf16_f32 v60, v60, s0
	ds_write_b16 v4, v60 offset:29568
	v_cvt_pk_bf16_f32 v61, v61, s0
	ds_write_b16 v4, v61 offset:30096
	v_cvt_pk_bf16_f32 v62, v62, s0
	ds_write_b16 v4, v62 offset:30624
	v_cvt_pk_bf16_f32 v63, v63, s0
	ds_write_b16 v4, v63 offset:31152
	v_cvt_pk_bf16_f32 v64, v64, s0
	ds_write_b16 v4, v64 offset:31680
	v_cvt_pk_bf16_f32 v65, v65, s0
	ds_write_b16 v4, v65 offset:32208
	v_cvt_pk_bf16_f32 v66, v66, s0
	ds_write_b16 v4, v66 offset:32736
	v_cvt_pk_bf16_f32 v67, v67, s0
	ds_write_b16 v4, v67 offset:33264
	s_ashr_i32 s0, s0, 1
	s_andn2_b32 s0, s0, 31
	s_add_i32 s0, s0, s24
	v_or_b32_e32 v162, s0, v165
	v_mov_b64_e32 v[0:1], s[72:73]
	s_movk_i32 s0, 0x2800
	v_bfe_u32 v4, v75, 5, 1
	v_mad_i64_i32 v[0:1], s[0:1], v162, s0, v[0:1]
	v_lshl_add_u64 v[0:1], s[74:75], 1, v[0:1]
	v_lshlrev_b32_e32 v128, 4, v4
	v_lshl_add_u64 v[0:1], v[0:1], 0, v[128:129]
	s_mov_b64 s[0:1], 0x2400
	v_lshl_add_u64 v[2:3], v[0:1], 0, s[0:1]
	s_movk_i32 s0, 0x2000
	v_add_co_u32_e32 v0, vcc, s0, v0
	s_waitcnt lgkmcnt(0)
	s_nop 0
	v_addc_co_u32_e32 v1, vcc, 0, v1, vcc
	s_barrier
	flat_load_dwordx4 v[28:31], v[0:1] offset:1024
	flat_load_dwordx4 v[32:35], v[2:3] offset:32
	flat_load_dwordx4 v[36:39], v[2:3] offset:64
	flat_load_dwordx4 v[40:43], v[2:3] offset:96
	flat_load_dwordx4 v[44:47], v[2:3] offset:128
	flat_load_dwordx4 v[48:51], v[2:3] offset:160
	flat_load_dwordx4 v[52:55], v[2:3] offset:192
	flat_load_dwordx4 v[8:11], v[2:3] offset:224
	v_xor_b32_e32 v0, 32, v237
	v_cmp_lt_i32_e32 vcc, v0, v76
	v_lshlrev_b32_e32 v77, 5, v4
	v_lshlrev_b32_e32 v164, 3, v4
	v_cndmask_b32_e32 v0, v237, v0, vcc
	v_lshlrev_b32_e32 v167, 2, v0
	v_ashrrev_i32_e32 v163, 31, v162
	v_add_u32_e32 v128, 0, v128
	s_waitcnt vmcnt(0) lgkmcnt(0)
	v_lshlrev_b32_e32 v182, 16, v31
	v_lshlrev_b32_e32 v160, 16, v35
	v_lshlrev_b32_e32 v148, 16, v39
	v_lshlrev_b32_e32 v126, 16, v43
	v_lshlrev_b32_e32 v110, 16, v47
	v_lshlrev_b32_e32 v94, 16, v51
	v_and_b32_e32 v25, 0xffff0000, v55
	v_and_b32_e32 v17, 0xffff0000, v11
	v_and_b32_e32 v19, 0xffff0000, v10
	v_and_b32_e32 v21, 0xffff0000, v9
	v_and_b32_e32 v23, 0xffff0000, v8
	v_and_b32_e32 v27, 0xffff0000, v54
	v_lshlrev_b32_e32 v16, 16, v11
	v_lshlrev_b32_e32 v18, 16, v10
	v_mov_b32_e32 v2, v19
	v_mov_b32_e32 v3, v17
	v_lshlrev_b32_e32 v20, 16, v9
	v_lshlrev_b32_e32 v22, 16, v8
	v_mov_b32_e32 v10, v23
	v_mov_b32_e32 v11, v21
	v_lshlrev_b32_e32 v24, 16, v55
	v_lshlrev_b32_e32 v26, 16, v54
	v_mov_b32_e32 v56, v27
	v_mov_b32_e32 v57, v25
	v_mov_b32_e32 v0, v18
	v_mov_b32_e32 v1, v16
	v_pk_mul_f32 v[2:3], v[2:3], v[2:3]
	v_mov_b32_e32 v8, v22
	v_mov_b32_e32 v9, v20
	v_pk_mul_f32 v[10:11], v[10:11], v[10:11]
	v_mov_b32_e32 v54, v26
	v_mov_b32_e32 v55, v24
	v_pk_mul_f32 v[56:57], v[56:57], v[56:57]
	v_pk_fma_f32 v[80:81], v[0:1], v[0:1], v[2:3]
	global_load_dwordx4 v[0:3], v77, s[94:95] offset:464
	global_load_dwordx4 v[4:7], v77, s[94:95] offset:448
	v_pk_fma_f32 v[82:83], v[8:9], v[8:9], v[10:11]
	global_load_dwordx4 v[8:11], v77, s[94:95] offset:400
	global_load_dwordx4 v[12:15], v77, s[94:95] offset:384
	v_pk_fma_f32 v[84:85], v[54:55], v[54:55], v[56:57]
	v_lshlrev_b32_e32 v86, 16, v53
	v_and_b32_e32 v87, 0xffff0000, v53
	v_lshlrev_b32_e32 v90, 16, v52
	v_and_b32_e32 v91, 0xffff0000, v52
	v_and_b32_e32 v95, 0xffff0000, v51
	global_load_dwordx4 v[52:55], v77, s[94:95] offset:336
	global_load_dwordx4 v[56:59], v77, s[94:95] offset:320
	v_lshlrev_b32_e32 v98, 16, v50
	v_and_b32_e32 v99, 0xffff0000, v50
	v_lshlrev_b32_e32 v102, 16, v49
	v_and_b32_e32 v103, 0xffff0000, v49
	v_lshlrev_b32_e32 v106, 16, v48
	v_and_b32_e32 v107, 0xffff0000, v48
	v_and_b32_e32 v111, 0xffff0000, v47
	global_load_dwordx4 v[48:51], v77, s[94:95] offset:272
	global_load_dwordx4 v[60:63], v77, s[94:95] offset:256
	v_lshlrev_b32_e32 v114, 16, v46
	v_and_b32_e32 v115, 0xffff0000, v46
	v_lshlrev_b32_e32 v118, 16, v45
	v_and_b32_e32 v119, 0xffff0000, v45
	v_lshlrev_b32_e32 v122, 16, v44
	v_and_b32_e32 v123, 0xffff0000, v44
	v_and_b32_e32 v127, 0xffff0000, v43
	global_load_dwordx4 v[44:47], v77, s[94:95] offset:208
	global_load_dwordx4 v[64:67], v77, s[94:95] offset:192
	v_lshlrev_b32_e32 v144, 16, v42
	v_and_b32_e32 v145, 0xffff0000, v42
	v_lshlrev_b32_e32 v146, 16, v41
	v_and_b32_e32 v147, 0xffff0000, v41
	v_lshlrev_b32_e32 v142, 16, v40
	v_and_b32_e32 v143, 0xffff0000, v40
	v_and_b32_e32 v149, 0xffff0000, v39
	global_load_dwordx4 v[40:43], v77, s[94:95] offset:144
	global_load_dwordx4 v[68:71], v77, s[94:95] offset:128
	v_lshlrev_b32_e32 v140, 16, v38
	v_and_b32_e32 v141, 0xffff0000, v38
; __device__ __forceinline__ unsigned cvtpk(float lo, float hi) { f32x2 v = {lo, hi}; bf16x2_t b = __builtin_convertvector(v, bf16x2_t); return __builtin_bit_cast(unsigned, b); }
; __device__ __forceinline__ float bflo(unsigned w) { return __uint_as_float(w << 16); }
; __device__ __forceinline__ float bfhi(unsigned w) { return __uint_as_float(w & 0xffff0000u); }
; __global__ void __launch_bounds__(512, 2) mk_fwd(Args a) {
;     ...
;                         u32x4 qr[8]; float ss = 0.f;
; #pragma unroll
;                         for (int d0 = 0; d0 < 8; ++d0) { qr[d0] = *(const u32x4*)(qrow + 16 * d0);
; #pragma unroll
;                             for (int e = 0; e < 4; ++e) { const float lo = bflo(qr[d0][e]), hh = bfhi(qr[d0][e]); ss += lo * lo + hh * hh; } }
;                         ss += __shfl_xor(ss, 32);
;                         const float rstd = 1.0f / sqrtf(ss * (1.0f / 128.0f) + 1e-6f);
;                         bf16x8 qf[8];
; #pragma unroll
;                         for (int d0 = 0; d0 < 8; ++d0) { u32x4 o;
; #pragma unroll
;                             for (int e = 0; e < 4; ++e) o[e] = cvtpk(bflo(qr[d0][e]) * rstd * gq[16 * d0 + 2 * e], bfhi(qr[d0][e]) * rstd * gq[16 * d0 + 2 * e + 1]);
	v_lshlrev_b32_e32 v152, 16, v37
	v_and_b32_e32 v153, 0xffff0000, v37
	v_lshlrev_b32_e32 v156, 16, v36
	v_and_b32_e32 v157, 0xffff0000, v36
	v_and_b32_e32 v161, 0xffff0000, v35
	global_load_dwordx4 v[36:39], v77, s[94:95] offset:80
	global_load_dwordx4 v[72:75], v77, s[94:95] offset:64
	v_lshlrev_b32_e32 v170, 16, v34
	v_and_b32_e32 v171, 0xffff0000, v34
	v_lshlrev_b32_e32 v174, 16, v33
	v_and_b32_e32 v175, 0xffff0000, v33
	v_lshlrev_b32_e32 v178, 16, v32
	v_and_b32_e32 v179, 0xffff0000, v32
	global_load_dwordx4 v[32:35], v77, s[94:95] offset:16
	s_nop 0
	global_load_dwordx4 v[76:79], v77, s[94:95]
	v_and_b32_e32 v183, 0xffff0000, v31
	v_lshlrev_b32_e32 v188, 16, v29
	v_and_b32_e32 v189, 0xffff0000, v29
	v_lshlrev_b32_e32 v192, 16, v28
	v_and_b32_e32 v193, 0xffff0000, v28
	v_pk_mul_f32 v[184:185], v[182:183], v[182:183]
	v_lshlrev_b32_e32 v186, 16, v30
	v_and_b32_e32 v187, 0xffff0000, v30
	v_pk_mul_f32 v[190:191], v[188:189], v[188:189]
	v_pk_mul_f32 v[28:29], v[192:193], v[192:193]
	v_pk_mul_f32 v[30:31], v[186:187], v[186:187]
	v_add_f32_e32 v184, v184, v185
	v_add_f32_e32 v185, v190, v191
	v_add_f32_e32 v28, v28, v29
	v_add_f32_e32 v28, v28, v185
	v_add_f32_e32 v29, v30, v31
	v_pk_mul_f32 v[180:181], v[178:179], v[178:179]
	v_add_f32_e32 v28, v28, v29
	v_pk_mul_f32 v[176:177], v[174:175], v[174:175]
	v_add_f32_e32 v28, v28, v184
	v_add_f32_e32 v29, v180, v181
	v_pk_mul_f32 v[172:173], v[170:171], v[170:171]
	v_add_f32_e32 v28, v28, v29
	v_add_f32_e32 v29, v176, v177
	v_pk_mul_f32 v[168:169], v[160:161], v[160:161]
	v_add_f32_e32 v28, v28, v29
	v_add_f32_e32 v29, v172, v173
	v_pk_mul_f32 v[158:159], v[156:157], v[156:157]
	v_add_f32_e32 v28, v28, v29
	v_add_f32_e32 v29, v168, v169
	v_pk_mul_f32 v[154:155], v[152:153], v[152:153]
	v_add_f32_e32 v28, v28, v29
	v_add_f32_e32 v29, v158, v159
	v_pk_mul_f32 v[150:151], v[140:141], v[140:141]
	v_add_f32_e32 v28, v28, v29
	v_add_f32_e32 v29, v154, v155
	v_pk_mul_f32 v[138:139], v[148:149], v[148:149]
	v_add_f32_e32 v28, v28, v29
	v_add_f32_e32 v29, v150, v151
	v_pk_mul_f32 v[136:137], v[142:143], v[142:143]
	v_add_f32_e32 v28, v28, v29
	v_add_f32_e32 v29, v138, v139
	v_pk_mul_f32 v[134:135], v[146:147], v[146:147]
	v_add_f32_e32 v28, v28, v29
	v_add_f32_e32 v29, v136, v137
	v_pk_mul_f32 v[132:133], v[144:145], v[144:145]
	v_add_f32_e32 v28, v28, v29
	v_add_f32_e32 v29, v134, v135
	v_pk_mul_f32 v[130:131], v[126:127], v[126:127]
	v_add_f32_e32 v28, v28, v29
	v_add_f32_e32 v29, v132, v133
	v_pk_mul_f32 v[124:125], v[122:123], v[122:123]
	v_add_f32_e32 v28, v28, v29
	v_add_f32_e32 v29, v130, v131
	v_pk_mul_f32 v[120:121], v[118:119], v[118:119]
	v_add_f32_e32 v28, v28, v29
	v_add_f32_e32 v29, v124, v125
	v_pk_mul_f32 v[116:117], v[114:115], v[114:115]
	v_add_f32_e32 v28, v28, v29
	v_add_f32_e32 v29, v120, v121
	v_pk_mul_f32 v[112:113], v[110:111], v[110:111]
	v_add_f32_e32 v28, v28, v29
	v_add_f32_e32 v29, v116, v117
	v_pk_mul_f32 v[108:109], v[106:107], v[106:107]
	v_add_f32_e32 v28, v28, v29
	v_add_f32_e32 v29, v112, v113
	v_pk_mul_f32 v[104:105], v[102:103], v[102:103]
	v_add_f32_e32 v28, v28, v29
	v_add_f32_e32 v29, v108, v109
	v_pk_mul_f32 v[100:101], v[98:99], v[98:99]
	v_add_f32_e32 v28, v28, v29
	v_add_f32_e32 v29, v104, v105
	v_pk_mul_f32 v[96:97], v[94:95], v[94:95]
	v_add_f32_e32 v28, v28, v29
	v_add_f32_e32 v29, v100, v101
	v_pk_mul_f32 v[92:93], v[90:91], v[90:91]
	v_add_f32_e32 v28, v28, v29
	v_add_f32_e32 v29, v96, v97
	v_pk_mul_f32 v[88:89], v[86:87], v[86:87]
	v_add_f32_e32 v28, v28, v29
	v_add_f32_e32 v29, v92, v93
	v_add_f32_e32 v28, v28, v29
	v_add_f32_e32 v29, v88, v89
	v_add_f32_e32 v28, v28, v29
	v_add_f32_e32 v28, v28, v84
	v_add_f32_e32 v28, v28, v85
	v_add_f32_e32 v28, v28, v82
	v_add_f32_e32 v28, v28, v83
	v_add_f32_e32 v28, v28, v80
	v_add_f32_e32 v28, v28, v81
	ds_bpermute_b32 v29, v167, v28
	v_mov_b32_e32 v169, 0xf149f2ca
	s_waitcnt lgkmcnt(0)
	v_add_f32_e32 v28, v28, v29
	v_fmamk_f32 v28, v28, 0x3c000000, v234
	v_cmp_gt_f32_e32 vcc, s33, v28
	v_mul_f32_e32 v29, 0x4f800000, v28
	s_nop 0
	v_cndmask_b32_e32 v28, v28, v29, vcc
	v_sqrt_f32_e32 v29, v28
	s_nop 0
	v_add_u32_e32 v30, -1, v29
	v_fma_f32 v31, -v30, v29, v28
	v_cmp_ge_f32_e64 s[6:7], 0, v31
	v_add_u32_e32 v31, 1, v29
	s_nop 0
	v_cndmask_b32_e64 v30, v29, v30, s[6:7]
	v_fma_f32 v29, -v31, v29, v28
	v_cmp_lt_f32_e64 s[6:7], 0, v29
	s_nop 1
	v_cndmask_b32_e64 v29, v30, v31, s[6:7]
	v_mul_f32_e32 v30, 0x37800000, v29
	v_cndmask_b32_e32 v29, v29, v30, vcc
	v_cmp_class_f32_e32 vcc, v28, v235
	s_nop 1
	v_cndmask_b32_e32 v28, v29, v28, vcc
	v_div_scale_f32 v29, s[0:1], v28, v28, 1.0
	v_rcp_f32_e32 v30, v29
	s_mov_b64 s[0:1], -1
	v_fma_f32 v31, -v29, v30, 1.0
	v_fmac_f32_e32 v30, v31, v30
	v_div_scale_f32 v31, vcc, 1.0, v28, 1.0
	v_mul_f32_e32 v80, v31, v30
	v_fma_f32 v81, -v29, v80, v31
	v_fmac_f32_e32 v80, v81, v30
	v_fma_f32 v29, -v29, v80, v31
	v_div_fmas_f32 v29, v29, v30, v80
	v_div_fixup_f32 v28, v29, v28, 1.0
	v_pk_mul_f32 v[30:31], v[28:29], v[192:193] op_sel_hi:[0,1]
	s_waitcnt vmcnt(0)
; __device__ __forceinline__ unsigned cvtpk(float lo, float hi) { f32x2 v = {lo, hi}; bf16x2_t b = __builtin_convertvector(v, bf16x2_t); return __builtin_bit_cast(unsigned, b); }
; __device__ __forceinline__ float bflo(unsigned w) { return __uint_as_float(w << 16); }
; __device__ __forceinline__ float bfhi(unsigned w) { return __uint_as_float(w & 0xffff0000u); }
; template <bool CAUSAL>
; __device__ __forceinline__ void attn_tile(const LAS unsigned char* Ks, const LAS unsigned char* Vts, const bf16x8 (&qf)[8], int qi, int r32, int hi, f32x16 (&O)[4], float& m2, float& l) {
;     const float c = 0.08838834764831845f * 1.4426950408889634f;
;     float m = -1.0e30f, lsum = 0.f;
; #pragma unroll
;     for (int d = 0; d < 4; ++d)
; #pragma unroll
;         for (int r = 0; r < 16; ++r) O[d][r] = 0.f;
; __global__ void __launch_bounds__(512, 2) mk_fwd(Args a) {
;     ...
;                         for (int d0 = 0; d0 < 8; ++d0) { u32x4 o;
; #pragma unroll
;                             for (int e = 0; e < 4; ++e) o[e] = cvtpk(bflo(qr[d0][e]) * rstd * gq[16 * d0 + 2 * e], bfhi(qr[d0][e]) * rstd * gq[16 * d0 + 2 * e + 1]);
;                             qf[d0] = __builtin_bit_cast(bf16x8, o); }
	v_pk_mul_f32 v[30:31], v[76:77], v[30:31]
	s_nop 0
	v_cvt_pk_bf16_f32 v130, v30, v31
	v_pk_mul_f32 v[30:31], v[28:29], v[188:189] op_sel_hi:[0,1]
	v_pk_mul_f32 v[30:31], v[78:79], v[30:31]
	s_nop 0
	v_cvt_pk_bf16_f32 v131, v30, v31
	v_pk_mul_f32 v[30:31], v[28:29], v[186:187] op_sel_hi:[0,1]
	v_pk_mul_f32 v[30:31], v[32:33], v[30:31]
	v_mov_b32_e32 v32, 0
	v_cvt_pk_bf16_f32 v132, v30, v31
	v_pk_mul_f32 v[30:31], v[28:29], v[182:183] op_sel_hi:[0,1]
	v_pk_mul_f32 v[30:31], v[34:35], v[30:31]
	v_mov_b32_e32 v33, v166
	v_cvt_pk_bf16_f32 v133, v30, v31
	v_pk_mul_f32 v[30:31], v[28:29], v[178:179] op_sel_hi:[0,1]
	v_pk_mul_f32 v[30:31], v[72:73], v[30:31]
	v_mov_b32_e32 v34, v166
	v_cvt_pk_bf16_f32 v134, v30, v31
	v_pk_mul_f32 v[30:31], v[28:29], v[174:175] op_sel_hi:[0,1]
	v_pk_mul_f32 v[30:31], v[74:75], v[30:31]
	v_mov_b32_e32 v35, v166
	v_cvt_pk_bf16_f32 v135, v30, v31
	v_pk_mul_f32 v[30:31], v[28:29], v[170:171] op_sel_hi:[0,1]
	v_pk_mul_f32 v[30:31], v[36:37], v[30:31]
	v_mov_b32_e32 v36, v166
	v_cvt_pk_bf16_f32 v136, v30, v31
	v_pk_mul_f32 v[30:31], v[28:29], v[160:161] op_sel_hi:[0,1]
	v_pk_mul_f32 v[30:31], v[38:39], v[30:31]
	v_mov_b32_e32 v37, v166
	v_cvt_pk_bf16_f32 v137, v30, v31
	v_pk_mul_f32 v[30:31], v[28:29], v[156:157] op_sel_hi:[0,1]
	v_pk_mul_f32 v[30:31], v[68:69], v[30:31]
	v_mov_b32_e32 v38, v166
	v_cvt_pk_bf16_f32 v138, v30, v31
	v_pk_mul_f32 v[30:31], v[28:29], v[152:153] op_sel_hi:[0,1]
	v_pk_mul_f32 v[30:31], v[70:71], v[30:31]
	v_mov_b32_e32 v39, v166
	v_cvt_pk_bf16_f32 v139, v30, v31
	v_pk_mul_f32 v[30:31], v[28:29], v[140:141] op_sel_hi:[0,1]
	v_pk_mul_f32 v[30:31], v[40:41], v[30:31]
	v_mov_b32_e32 v40, v166
	v_cvt_pk_bf16_f32 v140, v30, v31
	v_pk_mul_f32 v[30:31], v[28:29], v[148:149] op_sel_hi:[0,1]
	v_pk_mul_f32 v[30:31], v[42:43], v[30:31]
	v_mov_b32_e32 v41, v166
	v_cvt_pk_bf16_f32 v141, v30, v31
	v_pk_mul_f32 v[30:31], v[28:29], v[142:143] op_sel_hi:[0,1]
	v_pk_mul_f32 v[30:31], v[64:65], v[30:31]
	v_mov_b32_e32 v42, v166
	v_cvt_pk_bf16_f32 v142, v30, v31
	v_pk_mul_f32 v[30:31], v[28:29], v[146:147] op_sel_hi:[0,1]
	v_pk_mul_f32 v[30:31], v[66:67], v[30:31]
	v_mov_b32_e32 v43, v166
	v_cvt_pk_bf16_f32 v143, v30, v31
	v_pk_mul_f32 v[30:31], v[28:29], v[144:145] op_sel_hi:[0,1]
	v_pk_mul_f32 v[30:31], v[44:45], v[30:31]
	v_mov_b32_e32 v44, v166
	v_cvt_pk_bf16_f32 v144, v30, v31
	v_pk_mul_f32 v[30:31], v[28:29], v[126:127] op_sel_hi:[0,1]
	v_pk_mul_f32 v[30:31], v[46:47], v[30:31]
	v_mov_b32_e32 v45, v166
	v_cvt_pk_bf16_f32 v145, v30, v31
	v_pk_mul_f32 v[30:31], v[28:29], v[122:123] op_sel_hi:[0,1]
	v_pk_mul_f32 v[30:31], v[60:61], v[30:31]
	v_mov_b32_e32 v46, v166
	v_cvt_pk_bf16_f32 v146, v30, v31
	v_pk_mul_f32 v[30:31], v[28:29], v[118:119] op_sel_hi:[0,1]
	v_pk_mul_f32 v[30:31], v[62:63], v[30:31]
	v_mov_b32_e32 v47, v166
	v_cvt_pk_bf16_f32 v147, v30, v31
	v_pk_mul_f32 v[30:31], v[28:29], v[114:115] op_sel_hi:[0,1]
	v_pk_mul_f32 v[30:31], v[48:49], v[30:31]
	v_mov_b32_e32 v48, 0
	v_cvt_pk_bf16_f32 v148, v30, v31
	v_pk_mul_f32 v[30:31], v[28:29], v[110:111] op_sel_hi:[0,1]
	v_pk_mul_f32 v[30:31], v[50:51], v[30:31]
	v_mov_b32_e32 v49, v166
	v_cvt_pk_bf16_f32 v149, v30, v31
	v_pk_mul_f32 v[30:31], v[28:29], v[106:107] op_sel_hi:[0,1]
	v_pk_mul_f32 v[30:31], v[56:57], v[30:31]
	v_mov_b32_e32 v50, v166
	v_cvt_pk_bf16_f32 v150, v30, v31
	v_pk_mul_f32 v[30:31], v[28:29], v[102:103] op_sel_hi:[0,1]
	v_pk_mul_f32 v[30:31], v[58:59], v[30:31]
	v_mov_b32_e32 v51, v166
	v_cvt_pk_bf16_f32 v151, v30, v31
	v_pk_mul_f32 v[30:31], v[28:29], v[98:99] op_sel_hi:[0,1]
	v_pk_mul_f32 v[30:31], v[52:53], v[30:31]
	v_mov_b32_e32 v52, v166
	v_cvt_pk_bf16_f32 v152, v30, v31
	v_pk_mul_f32 v[30:31], v[28:29], v[94:95] op_sel_hi:[0,1]
	v_pk_mul_f32 v[30:31], v[54:55], v[30:31]
	v_mov_b32_e32 v53, v166
	v_cvt_pk_bf16_f32 v153, v30, v31
	v_pk_mul_f32 v[30:31], v[28:29], v[90:91] op_sel_hi:[0,1]
	v_pk_mul_f32 v[12:13], v[12:13], v[30:31]
	v_mov_b32_e32 v30, v166
	v_cvt_pk_bf16_f32 v154, v12, v13
	v_pk_mul_f32 v[12:13], v[28:29], v[86:87] op_sel_hi:[0,1]
	v_pk_mul_f32 v[12:13], v[14:15], v[12:13]
	v_mov_b32_e32 v14, v166
	v_cvt_pk_bf16_f32 v155, v12, v13
	v_pk_mul_f32 v[12:13], v[28:29], v[26:27] op_sel_hi:[0,1]
	v_pk_mul_f32 v[8:9], v[8:9], v[12:13]
	v_mov_b32_e32 v12, v166
	v_cvt_pk_bf16_f32 v156, v8, v9
	v_pk_mul_f32 v[8:9], v[28:29], v[24:25] op_sel_hi:[0,1]
	v_pk_mul_f32 v[8:9], v[10:11], v[8:9]
	v_mov_b32_e32 v10, v166
	v_cvt_pk_bf16_f32 v157, v8, v9
	v_pk_mul_f32 v[8:9], v[28:29], v[22:23] op_sel_hi:[0,1]
	v_pk_mul_f32 v[4:5], v[4:5], v[8:9]
	v_mov_b32_e32 v8, v166
	v_cvt_pk_bf16_f32 v158, v4, v5
	v_pk_mul_f32 v[4:5], v[28:29], v[20:21] op_sel_hi:[0,1]
	v_pk_mul_f32 v[4:5], v[6:7], v[4:5]
	v_mov_b32_e32 v6, v166
	v_cvt_pk_bf16_f32 v159, v4, v5
	v_pk_mul_f32 v[4:5], v[28:29], v[18:19] op_sel_hi:[0,1]
	v_pk_mul_f32 v[0:1], v[0:1], v[4:5]
	v_mov_b32_e32 v4, v166
	v_cvt_pk_bf16_f32 v160, v0, v1
	v_pk_mul_f32 v[0:1], v[28:29], v[16:17] op_sel_hi:[0,1]
	v_pk_mul_f32 v[0:1], v[2:3], v[0:1]
	v_mov_b32_e32 v2, v166
	v_cvt_pk_bf16_f32 v161, v0, v1
	v_mul_u32_u24_e32 v0, 0x210, v165
	v_add3_u32 v168, s2, v164, v0
	v_mov_b32_e32 v0, 0
	v_mov_b32_e32 v1, v166
	v_mov_b32_e32 v3, v166
	v_mov_b32_e32 v5, v166
	v_mov_b32_e32 v7, v166
	v_mov_b32_e32 v9, v166
	v_mov_b32_e32 v11, v166
	v_mov_b32_e32 v13, v166
	v_mov_b32_e32 v15, v166
	v_mov_b32_e32 v16, 0
	v_mov_b32_e32 v17, v166
	v_mov_b32_e32 v18, v166
	v_mov_b32_e32 v19, v166
	v_mov_b32_e32 v20, v166
	v_mov_b32_e32 v21, v166
	v_mov_b32_e32 v22, v166
	v_mov_b32_e32 v23, v166
	v_mov_b32_e32 v24, v166
	v_mov_b32_e32 v25, v166
	v_mov_b32_e32 v26, v166
	v_mov_b32_e32 v27, v166
	v_mov_b32_e32 v28, v166
	v_mov_b32_e32 v29, v166
	v_mov_b32_e32 v31, v166
	v_mov_b32_e32 v54, v166
	v_mov_b32_e32 v55, v166
	v_mov_b32_e32 v56, v166
	v_mov_b32_e32 v57, v166
	v_mov_b32_e32 v58, v166
	v_mov_b32_e32 v59, v166
	v_mov_b32_e32 v60, v166
	v_mov_b32_e32 v61, v166
	v_mov_b32_e32 v62, v166
	v_mov_b32_e32 v63, v166

; __device__ __forceinline__ float row_rstd(const float* ssq, int row, int fq) {
;     const f32x4* p = (const f32x4*)(ssq + (size_t)row * 32 + fq * 8);
;     const f32x4 a = p[0], b = p[1];
;     float s = ((a[0] + a[1]) + (a[2] + a[3])) + ((b[0] + b[1]) + (b[2] + b[3]));
;     s += __shfl_xor(s, 16); s += __shfl_xor(s, 32);
;     return 1.0f / sqrtf(s * (1.0f / 2048.0f) + 1e-6f);
;     __device__ __forceinline__ void operator()(const f32x4 (&acc)[2][2][4][2], const Unit& u, int wr, int wc, int fr, int fq) const {
;     ...
;         if (u.pm != last_pm) { last_pm = u.pm;
; #pragma unroll
;             for (int ai = 0; ai < 2; ++ai)
; #pragma unroll
;                 for (int m = 0; m < 4; ++m) rs[ai][m] = row_rstd(ssq, row0 + ai * HALF + m * 16, fq); }
.LBB0_427:
	v_lshl_add_u32 v180, s12, 8, v186
	v_add_u32_e32 v168, 0xa0, v180
	v_add_u32_e32 v166, 0xb0, v180
	v_or_b32_e32 v178, 16, v180
	v_or_b32_e32 v176, 32, v180
	v_or_b32_e32 v174, 48, v180
	v_add_u32_e32 v172, 0x80, v180
	v_readlane_b32 s72, v255, 9
	s_mov_b64 s[8:9], -1
	s_cmp_lg_u32 s12, s74
	v_ashrrev_i32_e32 v181, 31, v180
	v_ashrrev_i32_e32 v169, 31, v168
	v_ashrrev_i32_e32 v167, 31, v166
	v_ashrrev_i32_e32 v179, 31, v178
	v_ashrrev_i32_e32 v177, 31, v176
	v_ashrrev_i32_e32 v175, 31, v174
	v_ashrrev_i32_e32 v173, 31, v172
	v_add_u32_e32 v170, 0x90, v180
	v_readlane_b32 s95, v255, 8
	v_readlane_b32 s73, v255, 10
	s_cbranch_scc0 .LBB0_429
	v_and_b32_e32 v134, 64, v237
	v_xor_b32_e32 v128, 16, v237
	v_add_u32_e32 v134, 64, v134
	v_cmp_lt_i32_e32 vcc, v128, v134
	s_nop 1
	v_cndmask_b32_e32 v128, v237, v128, vcc
	v_lshlrev_b32_e32 v137, 2, v128
	v_xor_b32_e32 v128, 32, v237
	v_cmp_lt_i32_e32 vcc, v128, v134
	v_mov_b32_e32 v226, v168
	v_mov_b32_e32 v227, 0
	v_lshlrev_b64 v[226:227], 7, v[226:227]
	v_lshl_add_u64 v[226:227], v[154:155], 0, v[226:227]
	global_load_dwordx4 v[194:197], v[226:227], off
	global_load_dwordx4 v[198:201], v[226:227], off offset:16
	v_mov_b32_e32 v226, v166
	v_mov_b32_e32 v227, 0
	v_lshlrev_b64 v[226:227], 7, v[226:227]
	v_lshl_add_u64 v[226:227], v[154:155], 0, v[226:227]
	global_load_dwordx4 v[202:205], v[226:227], off
	global_load_dwordx4 v[206:209], v[226:227], off offset:16
	v_mov_b32_e32 v226, v180
	v_mov_b32_e32 v227, 0
	v_lshlrev_b64 v[226:227], 7, v[226:227]
	v_lshl_add_u64 v[226:227], v[154:155], 0, v[226:227]
	global_load_dwordx4 v[210:213], v[226:227], off
	global_load_dwordx4 v[214:217], v[226:227], off offset:16
	v_mov_b32_e32 v226, v178
	v_mov_b32_e32 v227, 0
	v_lshlrev_b64 v[226:227], 7, v[226:227]
	v_lshl_add_u64 v[226:227], v[154:155], 0, v[226:227]
	global_load_dwordx4 v[218:221], v[226:227], off
	global_load_dwordx4 v[222:225], v[226:227], off offset:16
	v_cndmask_b32_e32 v128, v237, v128, vcc
	v_lshlrev_b32_e32 v128, 2, v128
	s_waitcnt vmcnt(6) lgkmcnt(0)
	v_mov_b32_e32 v138, v194
	v_mov_b32_e32 v139, v195
	v_mov_b32_e32 v140, v196
	v_mov_b32_e32 v141, v197
	v_mov_b32_e32 v142, v198
	v_mov_b32_e32 v143, v199
	v_mov_b32_e32 v144, v200
	v_mov_b32_e32 v145, v201
	v_mov_b32_e32 v134, v138
	v_mov_b32_e32 v135, v142
	v_mov_b32_e32 v142, v139
	v_mov_b32_e32 v138, v140
	v_mov_b32_e32 v139, v144
	v_mov_b32_e32 v144, v141
	v_pk_add_f32 v[134:135], v[134:135], v[142:143]
	v_pk_add_f32 v[138:139], v[138:139], v[144:145]
	s_nop 0
	v_pk_add_f32 v[134:135], v[134:135], v[138:139]
	s_nop 0
	v_add_f32_e32 v134, v134, v135
	ds_bpermute_b32 v135, v137, v134
	s_waitcnt lgkmcnt(0)
	v_add_f32_e32 v134, v134, v135
	ds_bpermute_b32 v135, v128, v134
	s_waitcnt lgkmcnt(0)
	v_add_f32_e32 v134, v134, v135
	v_fmamk_f32 v134, v134, 0x3a000000, v234
	v_cmp_gt_f32_e32 vcc, s33, v134
	v_mul_f32_e32 v135, 0x4f800000, v134
	s_nop 0
	v_cndmask_b32_e32 v134, v134, v135, vcc
	v_sqrt_f32_e32 v135, v134
	s_nop 0
	v_add_u32_e32 v136, -1, v135
	v_fma_f32 v138, -v136, v135, v134
	v_cmp_ge_f32_e64 s[8:9], 0, v138
	v_add_u32_e32 v138, 1, v135
	s_nop 0
	v_cndmask_b32_e64 v136, v135, v136, s[8:9]
	v_fma_f32 v135, -v138, v135, v134
	v_cmp_lt_f32_e64 s[8:9], 0, v135
	s_nop 1
	v_cndmask_b32_e64 v135, v136, v138, s[8:9]
	v_mul_f32_e32 v136, 0x37800000, v135
	v_cndmask_b32_e32 v135, v135, v136, vcc
	v_cmp_class_f32_e32 vcc, v134, v235
	s_nop 1
	v_cndmask_b32_e32 v136, v135, v134, vcc
	s_waitcnt vmcnt(4) lgkmcnt(0)
	v_mov_b32_e32 v138, v202
	v_mov_b32_e32 v139, v203
	v_mov_b32_e32 v140, v204
	v_mov_b32_e32 v141, v205
	v_mov_b32_e32 v142, v206
	v_mov_b32_e32 v143, v207
	v_mov_b32_e32 v144, v208
	v_mov_b32_e32 v145, v209
	v_mov_b32_e32 v134, v138
	v_mov_b32_e32 v135, v142
	v_mov_b32_e32 v142, v139
	v_mov_b32_e32 v138, v140
	v_mov_b32_e32 v139, v144
	v_mov_b32_e32 v144, v141
	v_pk_add_f32 v[134:135], v[134:135], v[142:143]
	v_pk_add_f32 v[138:139], v[138:139], v[144:145]
	s_nop 0
	v_pk_add_f32 v[134:135], v[134:135], v[138:139]
	s_nop 0
	v_add_f32_e32 v134, v134, v135
	ds_bpermute_b32 v135, v137, v134
	s_waitcnt lgkmcnt(0)
	v_add_f32_e32 v134, v134, v135
	ds_bpermute_b32 v135, v128, v134
	s_waitcnt lgkmcnt(0)
	v_add_f32_e32 v134, v134, v135
	v_fmamk_f32 v134, v134, 0x3a000000, v234
	v_cmp_gt_f32_e32 vcc, s33, v134
	v_mul_f32_e32 v135, 0x4f800000, v134
	s_nop 0
	v_cndmask_b32_e32 v134, v134, v135, vcc
	v_sqrt_f32_e32 v135, v134
	s_nop 0
	v_add_u32_e32 v138, -1, v135
	v_fma_f32 v139, -v138, v135, v134
	v_cmp_ge_f32_e64 s[8:9], 0, v139
	v_add_u32_e32 v139, 1, v135
	s_nop 0
	v_cndmask_b32_e64 v138, v135, v138, s[8:9]
	v_fma_f32 v135, -v139, v135, v134
	v_cmp_lt_f32_e64 s[8:9], 0, v135
	s_nop 1
	v_cndmask_b32_e64 v135, v138, v139, s[8:9]
	v_mul_f32_e32 v138, 0x37800000, v135
	v_cndmask_b32_e32 v135, v135, v138, vcc
	v_cmp_class_f32_e32 vcc, v134, v235
	s_nop 1
	v_cndmask_b32_e32 v134, v135, v134, vcc
	v_div_scale_f32 v135, s[8:9], v134, v134, 1.0
	v_rcp_f32_e32 v138, v135
	s_nop 0
	v_fma_f32 v139, -v135, v138, 1.0
	v_fmac_f32_e32 v138, v139, v138
	v_div_scale_f32 v139, vcc, 1.0, v134, 1.0
	v_mul_f32_e32 v140, v139, v138
	v_fma_f32 v141, -v135, v140, v139
	v_fmac_f32_e32 v140, v141, v138
	v_fma_f32 v135, -v135, v140, v139
	v_div_fmas_f32 v135, v135, v138, v140
	v_div_fixup_f32 v135, v135, v134, 1.0
	v_div_scale_f32 v134, s[8:9], v136, v136, 1.0
	v_rcp_f32_e32 v138, v134
	s_nop 0
	v_fma_f32 v139, -v134, v138, 1.0
	v_fmac_f32_e32 v138, v139, v138
	v_div_scale_f32 v139, vcc, 1.0, v136, 1.0
	v_mul_f32_e32 v140, v139, v138
	v_fma_f32 v141, -v134, v140, v139
	v_fmac_f32_e32 v140, v141, v138
	v_fma_f32 v134, -v134, v140, v139
	v_div_fmas_f32 v134, v134, v138, v140
	v_div_fixup_f32 v134, v134, v136, 1.0
	s_waitcnt vmcnt(2) lgkmcnt(0)
; __device__ __forceinline__ float row_rstd(const float* ssq, int row, int fq) {
;     const f32x4* p = (const f32x4*)(ssq + (size_t)row * 32 + fq * 8);
;     const f32x4 a = p[0], b = p[1];
;     float s = ((a[0] + a[1]) + (a[2] + a[3])) + ((b[0] + b[1]) + (b[2] + b[3]));
;     s += __shfl_xor(s, 16); s += __shfl_xor(s, 32);
;     return 1.0f / sqrtf(s * (1.0f / 2048.0f) + 1e-6f);
;     __device__ __forceinline__ void operator()(const f32x4 (&acc)[2][2][4][2], const Unit& u, int wr, int wc, int fr, int fq) const {
;     ...
;         if (u.pm != last_pm) { last_pm = u.pm;
; #pragma unroll
;             for (int ai = 0; ai < 2; ++ai)
; #pragma unroll
;                 for (int m = 0; m < 4; ++m) rs[ai][m] = row_rstd(ssq, row0 + ai * HALF + m * 16, fq); }
	v_mov_b32_e32 v138, v210
	v_mov_b32_e32 v139, v211
	v_mov_b32_e32 v140, v212
	v_mov_b32_e32 v141, v213
	v_mov_b32_e32 v142, v214
	v_mov_b32_e32 v143, v215
	v_mov_b32_e32 v144, v216
	v_mov_b32_e32 v145, v217
	v_mov_b32_e32 v182, v138
	v_mov_b32_e32 v183, v142
	v_mov_b32_e32 v142, v139
	v_pk_add_f32 v[138:139], v[182:183], v[142:143]
	v_mov_b32_e32 v142, v140
	v_mov_b32_e32 v143, v144
	v_mov_b32_e32 v144, v141
	v_pk_add_f32 v[140:141], v[142:143], v[144:145]
	s_nop 0
	v_pk_add_f32 v[138:139], v[138:139], v[140:141]
	s_nop 0
	v_add_f32_e32 v138, v138, v139
	ds_bpermute_b32 v139, v137, v138
	s_waitcnt lgkmcnt(0)
	v_add_f32_e32 v138, v138, v139
	ds_bpermute_b32 v139, v128, v138
	s_waitcnt lgkmcnt(0)
	v_add_f32_e32 v138, v138, v139
	v_fmamk_f32 v138, v138, 0x3a000000, v234
	v_cmp_gt_f32_e32 vcc, s33, v138
	v_mul_f32_e32 v139, 0x4f800000, v138
	s_nop 0
	v_cndmask_b32_e32 v138, v138, v139, vcc
	v_sqrt_f32_e32 v139, v138
	s_nop 0
	v_add_u32_e32 v140, -1, v139
	v_fma_f32 v141, -v140, v139, v138
	v_cmp_ge_f32_e64 s[8:9], 0, v141
	v_add_u32_e32 v141, 1, v139
	s_nop 0
	v_cndmask_b32_e64 v140, v139, v140, s[8:9]
	v_fma_f32 v139, -v141, v139, v138
	v_cmp_lt_f32_e64 s[8:9], 0, v139
	s_nop 1
	v_cndmask_b32_e64 v139, v140, v141, s[8:9]
	v_mul_f32_e32 v140, 0x37800000, v139
	v_cndmask_b32_e32 v139, v139, v140, vcc
	v_cmp_class_f32_e32 vcc, v138, v235
	s_nop 1
	v_cndmask_b32_e32 v171, v139, v138, vcc
	s_waitcnt vmcnt(0) lgkmcnt(0)
	v_mov_b32_e32 v138, v218
	v_mov_b32_e32 v139, v219
	v_mov_b32_e32 v140, v220
	v_mov_b32_e32 v141, v221
	v_mov_b32_e32 v142, v222
	v_mov_b32_e32 v143, v223
	v_mov_b32_e32 v144, v224
	v_mov_b32_e32 v145, v225
	v_mov_b32_e32 v182, v138
	v_mov_b32_e32 v183, v142
	v_mov_b32_e32 v142, v139
	v_pk_add_f32 v[138:139], v[182:183], v[142:143]
	v_mov_b32_e32 v142, v140
	v_mov_b32_e32 v143, v144
	v_mov_b32_e32 v144, v141
	v_pk_add_f32 v[140:141], v[142:143], v[144:145]
	s_nop 0
	v_pk_add_f32 v[138:139], v[138:139], v[140:141]
	s_nop 0
	v_add_f32_e32 v138, v138, v139
	ds_bpermute_b32 v139, v137, v138
	s_waitcnt lgkmcnt(0)
	v_add_f32_e32 v138, v138, v139
	ds_bpermute_b32 v139, v128, v138
	s_waitcnt lgkmcnt(0)
	v_add_f32_e32 v138, v138, v139
	v_fmamk_f32 v138, v138, 0x3a000000, v234
	v_cmp_gt_f32_e32 vcc, s33, v138
	v_mul_f32_e32 v139, 0x4f800000, v138
	s_nop 0
	v_cndmask_b32_e32 v138, v138, v139, vcc
	v_sqrt_f32_e32 v139, v138
	s_nop 0
	v_add_u32_e32 v140, -1, v139
	v_fma_f32 v141, -v140, v139, v138
	v_cmp_ge_f32_e64 s[8:9], 0, v141
	v_add_u32_e32 v141, 1, v139
	s_nop 0
	v_cndmask_b32_e64 v140, v139, v140, s[8:9]
	v_fma_f32 v139, -v141, v139, v138
	v_cmp_lt_f32_e64 s[8:9], 0, v139
	s_nop 1
	v_cndmask_b32_e64 v139, v140, v141, s[8:9]
	v_mul_f32_e32 v140, 0x37800000, v139
	v_cndmask_b32_e32 v139, v139, v140, vcc
	v_cmp_class_f32_e32 vcc, v138, v235
	s_nop 1
	v_cndmask_b32_e32 v138, v139, v138, vcc
	v_div_scale_f32 v139, s[8:9], v138, v138, 1.0
	v_rcp_f32_e32 v140, v139
	s_nop 0
	v_fma_f32 v141, -v139, v140, 1.0
	v_fmac_f32_e32 v140, v141, v140
	v_div_scale_f32 v141, vcc, 1.0, v138, 1.0
	v_mul_f32_e32 v142, v141, v140
	v_fma_f32 v143, -v139, v142, v141
	v_fmac_f32_e32 v142, v143, v140
	v_fma_f32 v139, -v139, v142, v141
	v_div_fmas_f32 v139, v139, v140, v142
	v_div_fixup_f32 v183, v139, v138, 1.0
	v_div_scale_f32 v138, s[8:9], v171, v171, 1.0
	v_rcp_f32_e32 v139, v138
	s_nop 0
	v_fma_f32 v140, -v138, v139, 1.0
	v_fmac_f32_e32 v139, v140, v139
	v_div_scale_f32 v140, vcc, 1.0, v171, 1.0
	v_mul_f32_e32 v141, v140, v139
	v_fma_f32 v142, -v138, v141, v140
	v_fmac_f32_e32 v141, v142, v139
	v_fma_f32 v138, -v138, v141, v140
	v_div_fmas_f32 v138, v138, v139, v141
	v_div_fixup_f32 v182, v138, v171, 1.0
	v_mov_b32_e32 v226, v176
	v_mov_b32_e32 v227, 0
	v_lshlrev_b64 v[226:227], 7, v[226:227]
	v_lshl_add_u64 v[226:227], v[154:155], 0, v[226:227]
	global_load_dwordx4 v[194:197], v[226:227], off
	global_load_dwordx4 v[198:201], v[226:227], off offset:16
	v_mov_b32_e32 v226, v174
	v_mov_b32_e32 v227, 0
	v_lshlrev_b64 v[226:227], 7, v[226:227]
	v_lshl_add_u64 v[226:227], v[154:155], 0, v[226:227]
	global_load_dwordx4 v[202:205], v[226:227], off
	global_load_dwordx4 v[206:209], v[226:227], off offset:16
	v_mov_b32_e32 v226, v172
	v_mov_b32_e32 v227, 0
	v_lshlrev_b64 v[226:227], 7, v[226:227]
	v_lshl_add_u64 v[226:227], v[154:155], 0, v[226:227]
	global_load_dwordx4 v[210:213], v[226:227], off
	global_load_dwordx4 v[214:217], v[226:227], off offset:16
	v_mov_b32_e32 v226, v170
	v_mov_b32_e32 v227, 0
	v_lshlrev_b64 v[226:227], 7, v[226:227]
	v_lshl_add_u64 v[226:227], v[154:155], 0, v[226:227]
	global_load_dwordx4 v[218:221], v[226:227], off
	global_load_dwordx4 v[222:225], v[226:227], off offset:16
	s_waitcnt vmcnt(6) lgkmcnt(0)
	v_mov_b32_e32 v138, v194
	v_mov_b32_e32 v139, v195
	v_mov_b32_e32 v140, v196
	v_mov_b32_e32 v141, v197
	v_mov_b32_e32 v142, v198
	v_mov_b32_e32 v143, v199
	v_mov_b32_e32 v144, v200
	v_mov_b32_e32 v145, v201
	v_mov_b32_e32 v184, v138
	v_mov_b32_e32 v185, v142
	v_mov_b32_e32 v142, v139
	v_pk_add_f32 v[138:139], v[184:185], v[142:143]
	v_mov_b32_e32 v142, v140
	v_mov_b32_e32 v143, v144
	v_mov_b32_e32 v144, v141
	v_pk_add_f32 v[140:141], v[142:143], v[144:145]
	s_nop 0
	v_pk_add_f32 v[138:139], v[138:139], v[140:141]
	s_nop 0
	v_add_f32_e32 v138, v138, v139
	ds_bpermute_b32 v139, v137, v138
	s_waitcnt lgkmcnt(0)
	v_add_f32_e32 v138, v138, v139
	ds_bpermute_b32 v139, v128, v138
	s_waitcnt lgkmcnt(0)
; __device__ __forceinline__ float row_rstd(const float* ssq, int row, int fq) {
;     const f32x4* p = (const f32x4*)(ssq + (size_t)row * 32 + fq * 8);
;     const f32x4 a = p[0], b = p[1];
;     float s = ((a[0] + a[1]) + (a[2] + a[3])) + ((b[0] + b[1]) + (b[2] + b[3]));
;     s += __shfl_xor(s, 16); s += __shfl_xor(s, 32);
;     return 1.0f / sqrtf(s * (1.0f / 2048.0f) + 1e-6f);
;     __device__ __forceinline__ void operator()(const f32x4 (&acc)[2][2][4][2], const Unit& u, int wr, int wc, int fr, int fq) const {
;     ...
;         if (u.pm != last_pm) { last_pm = u.pm;
; #pragma unroll
;             for (int ai = 0; ai < 2; ++ai)
; #pragma unroll
;                 for (int m = 0; m < 4; ++m) rs[ai][m] = row_rstd(ssq, row0 + ai * HALF + m * 16, fq); }
	v_add_f32_e32 v138, v138, v139
	v_fmamk_f32 v138, v138, 0x3a000000, v234
	v_cmp_gt_f32_e32 vcc, s33, v138
	v_mul_f32_e32 v139, 0x4f800000, v138
	s_nop 0
	v_cndmask_b32_e32 v138, v138, v139, vcc
	v_sqrt_f32_e32 v139, v138
	s_nop 0
	v_add_u32_e32 v140, -1, v139
	v_fma_f32 v141, -v140, v139, v138
	v_cmp_ge_f32_e64 s[8:9], 0, v141
	v_add_u32_e32 v141, 1, v139
	s_nop 0
	v_cndmask_b32_e64 v140, v139, v140, s[8:9]
	v_fma_f32 v139, -v141, v139, v138
	v_cmp_lt_f32_e64 s[8:9], 0, v139
	s_nop 1
	v_cndmask_b32_e64 v139, v140, v141, s[8:9]
	v_mul_f32_e32 v140, 0x37800000, v139
	v_cndmask_b32_e32 v139, v139, v140, vcc
	v_cmp_class_f32_e32 vcc, v138, v235
	s_nop 1
	v_cndmask_b32_e32 v171, v139, v138, vcc
	s_waitcnt vmcnt(4) lgkmcnt(0)
	v_mov_b32_e32 v138, v202
	v_mov_b32_e32 v139, v203
	v_mov_b32_e32 v140, v204
	v_mov_b32_e32 v141, v205
	v_mov_b32_e32 v142, v206
	v_mov_b32_e32 v143, v207
	v_mov_b32_e32 v144, v208
	v_mov_b32_e32 v145, v209
	v_mov_b32_e32 v184, v138
	v_mov_b32_e32 v185, v142
	v_mov_b32_e32 v142, v139
	v_pk_add_f32 v[138:139], v[184:185], v[142:143]
	v_mov_b32_e32 v142, v140
	v_mov_b32_e32 v143, v144
	v_mov_b32_e32 v144, v141
	v_pk_add_f32 v[140:141], v[142:143], v[144:145]
	s_nop 0
	v_pk_add_f32 v[138:139], v[138:139], v[140:141]
	s_nop 0
	v_add_f32_e32 v138, v138, v139
	ds_bpermute_b32 v139, v137, v138
	s_waitcnt lgkmcnt(0)
	v_add_f32_e32 v138, v138, v139
	ds_bpermute_b32 v139, v128, v138
	s_waitcnt lgkmcnt(0)
	v_add_f32_e32 v138, v138, v139
	v_fmamk_f32 v138, v138, 0x3a000000, v234
	v_cmp_gt_f32_e32 vcc, s33, v138
	v_mul_f32_e32 v139, 0x4f800000, v138
	s_nop 0
	v_cndmask_b32_e32 v138, v138, v139, vcc
	v_sqrt_f32_e32 v139, v138
	s_nop 0
	v_add_u32_e32 v140, -1, v139
	v_fma_f32 v141, -v140, v139, v138
	v_cmp_ge_f32_e64 s[8:9], 0, v141
	v_add_u32_e32 v141, 1, v139
	s_nop 0
	v_cndmask_b32_e64 v140, v139, v140, s[8:9]
	v_fma_f32 v139, -v141, v139, v138
	v_cmp_lt_f32_e64 s[8:9], 0, v139
	s_nop 1
	v_cndmask_b32_e64 v139, v140, v141, s[8:9]
	v_mul_f32_e32 v140, 0x37800000, v139
	v_cndmask_b32_e32 v139, v139, v140, vcc
	v_cmp_class_f32_e32 vcc, v138, v235
	s_nop 1
	v_cndmask_b32_e32 v138, v139, v138, vcc
	v_div_scale_f32 v139, s[8:9], v138, v138, 1.0
	v_rcp_f32_e32 v140, v139
	s_nop 0
	v_fma_f32 v141, -v139, v140, 1.0
	v_fmac_f32_e32 v140, v141, v140
	v_div_scale_f32 v141, vcc, 1.0, v138, 1.0
	v_mul_f32_e32 v142, v141, v140
	v_fma_f32 v143, -v139, v142, v141
	v_fmac_f32_e32 v142, v143, v140
	v_fma_f32 v139, -v139, v142, v141
	v_div_fmas_f32 v139, v139, v140, v142
	v_div_fixup_f32 v185, v139, v138, 1.0
	v_div_scale_f32 v138, s[8:9], v171, v171, 1.0
	v_rcp_f32_e32 v139, v138
	s_nop 0
	v_fma_f32 v140, -v138, v139, 1.0
	v_fmac_f32_e32 v139, v140, v139
	v_div_scale_f32 v140, vcc, 1.0, v171, 1.0
	v_mul_f32_e32 v141, v140, v139
	v_fma_f32 v142, -v138, v141, v140
	v_fmac_f32_e32 v141, v142, v139
	v_fma_f32 v138, -v138, v141, v140
	v_div_fmas_f32 v138, v138, v139, v141
	v_div_fixup_f32 v184, v138, v171, 1.0
	v_ashrrev_i32_e32 v171, 31, v170
	s_waitcnt vmcnt(2) lgkmcnt(0)
	v_mov_b32_e32 v138, v210
	v_mov_b32_e32 v139, v211
	v_mov_b32_e32 v140, v212
	v_mov_b32_e32 v141, v213
	v_mov_b32_e32 v142, v214
	v_mov_b32_e32 v143, v215
	v_mov_b32_e32 v144, v216
	v_mov_b32_e32 v145, v217
	v_mov_b32_e32 v190, v138
	v_mov_b32_e32 v191, v142
	v_mov_b32_e32 v142, v139
	v_pk_add_f32 v[138:139], v[190:191], v[142:143]
	v_mov_b32_e32 v142, v140
	v_mov_b32_e32 v143, v144
	v_mov_b32_e32 v144, v141
	v_pk_add_f32 v[140:141], v[142:143], v[144:145]
	s_nop 0
	v_pk_add_f32 v[138:139], v[138:139], v[140:141]
	s_nop 0
	v_add_f32_e32 v138, v138, v139
	ds_bpermute_b32 v139, v137, v138
	s_waitcnt lgkmcnt(0)
	v_add_f32_e32 v138, v138, v139
	ds_bpermute_b32 v139, v128, v138
	s_waitcnt lgkmcnt(0)
	v_add_f32_e32 v138, v138, v139
	v_fmamk_f32 v138, v138, 0x3a000000, v234
	v_cmp_gt_f32_e32 vcc, s33, v138
	v_mul_f32_e32 v139, 0x4f800000, v138
	s_nop 0
	v_cndmask_b32_e32 v138, v138, v139, vcc
	v_sqrt_f32_e32 v139, v138
	s_nop 0
	v_add_u32_e32 v140, -1, v139
	v_fma_f32 v141, -v140, v139, v138
	v_cmp_ge_f32_e64 s[8:9], 0, v141
	v_add_u32_e32 v141, 1, v139
	s_nop 0
	v_cndmask_b32_e64 v140, v139, v140, s[8:9]
	v_fma_f32 v139, -v141, v139, v138
	v_cmp_lt_f32_e64 s[8:9], 0, v139
	s_nop 1
	v_cndmask_b32_e64 v139, v140, v141, s[8:9]
	v_mul_f32_e32 v140, 0x37800000, v139
	v_cndmask_b32_e32 v139, v139, v140, vcc
	v_cmp_class_f32_e32 vcc, v138, v235
	s_nop 1
	v_cndmask_b32_e32 v190, v139, v138, vcc
	s_waitcnt vmcnt(0) lgkmcnt(0)
	v_mov_b32_e32 v142, v218
	v_mov_b32_e32 v143, v219
	v_mov_b32_e32 v144, v220
	v_mov_b32_e32 v145, v221
	v_mov_b32_e32 v138, v222
	v_mov_b32_e32 v139, v223
	v_mov_b32_e32 v140, v224
	v_mov_b32_e32 v141, v225
	v_mov_b32_e32 v192, v142
	v_mov_b32_e32 v193, v138
	v_mov_b32_e32 v138, v143
	v_mov_b32_e32 v142, v144
	v_mov_b32_e32 v143, v140
	v_mov_b32_e32 v140, v145
	v_pk_add_f32 v[138:139], v[192:193], v[138:139]
	v_pk_add_f32 v[140:141], v[142:143], v[140:141]
	s_nop 0
	v_pk_add_f32 v[138:139], v[138:139], v[140:141]
	s_nop 0
	v_add_f32_e32 v138, v138, v139
	ds_bpermute_b32 v137, v137, v138
	s_waitcnt lgkmcnt(0)
	v_add_f32_e32 v137, v138, v137
	ds_bpermute_b32 v128, v128, v137
	s_waitcnt lgkmcnt(0)
	v_add_f32_e32 v128, v137, v128
	v_fmamk_f32 v128, v128, 0x3a000000, v234
	v_cmp_gt_f32_e32 vcc, s33, v128
	v_mul_f32_e32 v137, 0x4f800000, v128
	s_nop 0
	v_cndmask_b32_e32 v128, v128, v137, vcc
	v_sqrt_f32_e32 v137, v128
	s_nop 0
	v_add_u32_e32 v138, -1, v137
	v_fma_f32 v139, -v138, v137, v128
	v_cmp_ge_f32_e64 s[8:9], 0, v139
	v_add_u32_e32 v139, 1, v137
	s_nop 0
	v_cndmask_b32_e64 v138, v137, v138, s[8:9]
	v_fma_f32 v137, -v139, v137, v128
	v_cmp_lt_f32_e64 s[8:9], 0, v137
	s_nop 1
	v_cndmask_b32_e64 v137, v138, v139, s[8:9]
	v_mul_f32_e32 v138, 0x37800000, v137
	v_cndmask_b32_e32 v137, v137, v138, vcc
	v_cmp_class_f32_e32 vcc, v128, v235
	s_nop 1
	v_cndmask_b32_e32 v128, v137, v128, vcc
	v_div_scale_f32 v137, s[8:9], v128, v128, 1.0
	v_rcp_f32_e32 v138, v137
	s_nop 0
	v_fma_f32 v139, -v137, v138, 1.0
	v_fmac_f32_e32 v138, v139, v138
	v_div_scale_f32 v139, vcc, 1.0, v128, 1.0
	v_mul_f32_e32 v140, v139, v138
	v_fma_f32 v141, -v137, v140, v139
	v_fmac_f32_e32 v140, v141, v138
	v_fma_f32 v137, -v137, v140, v139
	v_div_fmas_f32 v137, v137, v138, v140
	v_div_fixup_f32 v139, v137, v128, 1.0
	v_div_scale_f32 v128, s[8:9], v190, v190, 1.0
	v_rcp_f32_e32 v137, v128
	s_mov_b64 s[8:9], 0
	v_fma_f32 v138, -v128, v137, 1.0
	v_fmac_f32_e32 v137, v138, v137
	v_div_scale_f32 v138, vcc, 1.0, v190, 1.0
	v_mul_f32_e32 v140, v138, v137
	v_fma_f32 v141, -v128, v140, v138
	v_fmac_f32_e32 v140, v141, v137
	v_fma_f32 v128, -v128, v140, v138
	v_div_fmas_f32 v128, v128, v137, v140
	v_div_fixup_f32 v138, v128, v190, 1.0

; __device__ __forceinline__ float row_rstd(const float* ssq, int row, int fq) {
;     const f32x4* p = (const f32x4*)(ssq + (size_t)row * 32 + fq * 8);
;     const f32x4 a = p[0], b = p[1];
;     float s = ((a[0] + a[1]) + (a[2] + a[3])) + ((b[0] + b[1]) + (b[2] + b[3]));
;     s += __shfl_xor(s, 16); s += __shfl_xor(s, 32);
;     return 1.0f / sqrtf(s * (1.0f / 2048.0f) + 1e-6f);
;     __device__ __forceinline__ void operator()(const f32x4 (&acc)[2][2][4][2], const Unit& u, int wr, int wc, int fr, int fq) const {
;     ...
;         if (u.pm != last_pm) { last_pm = u.pm;
; #pragma unroll
;             for (int ai = 0; ai < 2; ++ai)
; #pragma unroll
;                 for (int m = 0; m < 4; ++m) rs[ai][m] = row_rstd(ssq, row0 + ai * HALF + m * 16, fq); }
.LBB0_593:
	v_lshl_add_u32 v184, s4, 8, v186
	v_add_u32_e32 v162, 0xa0, v184
	v_add_u32_e32 v160, 0xb0, v184
	v_or_b32_e32 v180, 16, v184
	v_or_b32_e32 v178, 32, v184
	v_or_b32_e32 v176, 48, v184
	v_add_u32_e32 v168, 0x80, v184
	s_mov_b64 s[0:1], -1
	s_cmp_lg_u32 s4, s25
	v_ashrrev_i32_e32 v185, 31, v184
	v_ashrrev_i32_e32 v163, 31, v162
	v_ashrrev_i32_e32 v161, 31, v160
	v_ashrrev_i32_e32 v181, 31, v180
	v_ashrrev_i32_e32 v179, 31, v178
	v_ashrrev_i32_e32 v177, 31, v176
	v_ashrrev_i32_e32 v169, 31, v168
	v_add_u32_e32 v164, 0x90, v184
	s_cbranch_scc0 .LBB0_595
	v_and_b32_e32 v57, 64, v237
	v_xor_b32_e32 v56, 16, v237
	v_add_u32_e32 v57, 64, v57
	v_cmp_lt_i32_e32 vcc, v56, v57
	s_nop 1
	v_cndmask_b32_e32 v56, v237, v56, vcc
	v_lshlrev_b32_e32 v128, 2, v56
	v_xor_b32_e32 v56, 32, v237
	v_cmp_lt_i32_e32 vcc, v56, v57
	s_nop 1
	v_cndmask_b32_e32 v56, v237, v56, vcc
	v_lshlrev_b32_e32 v59, 2, v56
	v_mov_b32_e32 v226, v162
	v_mov_b32_e32 v227, 0
	v_lshlrev_b64 v[226:227], 7, v[226:227]
	v_lshl_add_u64 v[226:227], v[154:155], 0, v[226:227]
	global_load_dwordx4 v[194:197], v[226:227], off
	global_load_dwordx4 v[198:201], v[226:227], off offset:16
	v_mov_b32_e32 v226, v160
	v_mov_b32_e32 v227, 0
	v_lshlrev_b64 v[226:227], 7, v[226:227]
	v_lshl_add_u64 v[226:227], v[154:155], 0, v[226:227]
	global_load_dwordx4 v[202:205], v[226:227], off
	global_load_dwordx4 v[206:209], v[226:227], off offset:16
	v_mov_b32_e32 v226, v184
	v_mov_b32_e32 v227, 0
	v_lshlrev_b64 v[226:227], 7, v[226:227]
	v_lshl_add_u64 v[226:227], v[154:155], 0, v[226:227]
	global_load_dwordx4 v[210:213], v[226:227], off
	global_load_dwordx4 v[214:217], v[226:227], off offset:16
	v_mov_b32_e32 v226, v180
	v_mov_b32_e32 v227, 0
	v_lshlrev_b64 v[226:227], 7, v[226:227]
	v_lshl_add_u64 v[226:227], v[154:155], 0, v[226:227]
	global_load_dwordx4 v[218:221], v[226:227], off
	global_load_dwordx4 v[222:225], v[226:227], off offset:16
	s_waitcnt vmcnt(6) lgkmcnt(0)
	v_mov_b32_e32 v138, v194
	v_mov_b32_e32 v139, v195
	v_mov_b32_e32 v140, v196
	v_mov_b32_e32 v141, v197
	v_mov_b32_e32 v142, v198
	v_mov_b32_e32 v143, v199
	v_mov_b32_e32 v144, v200
	v_mov_b32_e32 v145, v201
	v_mov_b32_e32 v56, v138
	v_mov_b32_e32 v57, v142
	v_mov_b32_e32 v142, v139
	v_mov_b32_e32 v138, v140
	v_mov_b32_e32 v139, v144
	v_mov_b32_e32 v144, v141
	v_pk_add_f32 v[56:57], v[56:57], v[142:143]
	v_pk_add_f32 v[138:139], v[138:139], v[144:145]
	s_nop 0
	v_pk_add_f32 v[56:57], v[56:57], v[138:139]
	s_nop 0
	v_add_f32_e32 v56, v56, v57
	ds_bpermute_b32 v57, v128, v56
	s_waitcnt lgkmcnt(0)
	v_add_f32_e32 v56, v56, v57
	ds_bpermute_b32 v57, v59, v56
	s_waitcnt lgkmcnt(0)
	v_add_f32_e32 v56, v56, v57
	v_fmamk_f32 v56, v56, 0x3a000000, v234
	v_cmp_gt_f32_e32 vcc, s33, v56
	v_mul_f32_e32 v57, 0x4f800000, v56
	s_nop 0
	v_cndmask_b32_e32 v56, v56, v57, vcc
	v_sqrt_f32_e32 v57, v56
	s_nop 0
	v_add_u32_e32 v58, -1, v57
	v_fma_f32 v138, -v58, v57, v56
	v_cmp_ge_f32_e64 s[8:9], 0, v138
	v_add_u32_e32 v138, 1, v57
	s_nop 0
	v_cndmask_b32_e64 v58, v57, v58, s[8:9]
	v_fma_f32 v57, -v138, v57, v56
	v_cmp_lt_f32_e64 s[8:9], 0, v57
	s_nop 1
	v_cndmask_b32_e64 v57, v58, v138, s[8:9]
	v_mul_f32_e32 v58, 0x37800000, v57
	v_cndmask_b32_e32 v57, v57, v58, vcc
	v_cmp_class_f32_e32 vcc, v56, v235
	s_nop 1
	v_cndmask_b32_e32 v58, v57, v56, vcc
	s_waitcnt vmcnt(4) lgkmcnt(0)
	v_mov_b32_e32 v138, v202
	v_mov_b32_e32 v139, v203
	v_mov_b32_e32 v140, v204
	v_mov_b32_e32 v141, v205
	v_mov_b32_e32 v142, v206
	v_mov_b32_e32 v143, v207
	v_mov_b32_e32 v144, v208
	v_mov_b32_e32 v145, v209
	v_mov_b32_e32 v56, v138
	v_mov_b32_e32 v57, v142
	v_mov_b32_e32 v142, v139
	v_mov_b32_e32 v138, v140
	v_mov_b32_e32 v139, v144
	v_mov_b32_e32 v144, v141
	v_pk_add_f32 v[56:57], v[56:57], v[142:143]
	v_pk_add_f32 v[138:139], v[138:139], v[144:145]
	s_nop 0
	v_pk_add_f32 v[56:57], v[56:57], v[138:139]
	s_nop 0
	v_add_f32_e32 v56, v56, v57
	ds_bpermute_b32 v57, v128, v56
	s_waitcnt lgkmcnt(0)
	v_add_f32_e32 v56, v56, v57
	ds_bpermute_b32 v57, v59, v56
	s_waitcnt lgkmcnt(0)
	v_add_f32_e32 v56, v56, v57
	v_fmamk_f32 v56, v56, 0x3a000000, v234
	v_cmp_gt_f32_e32 vcc, s33, v56
	v_mul_f32_e32 v57, 0x4f800000, v56
	s_nop 0
	v_cndmask_b32_e32 v56, v56, v57, vcc
	v_sqrt_f32_e32 v57, v56
	s_nop 0
	v_add_u32_e32 v138, -1, v57
	v_fma_f32 v139, -v138, v57, v56
	v_cmp_ge_f32_e64 s[8:9], 0, v139
	v_add_u32_e32 v139, 1, v57
	s_nop 0
	v_cndmask_b32_e64 v138, v57, v138, s[8:9]
	v_fma_f32 v57, -v139, v57, v56
	v_cmp_lt_f32_e64 s[8:9], 0, v57
	s_nop 1
	v_cndmask_b32_e64 v57, v138, v139, s[8:9]
	v_mul_f32_e32 v138, 0x37800000, v57
	v_cndmask_b32_e32 v57, v57, v138, vcc
	v_cmp_class_f32_e32 vcc, v56, v235
	s_nop 1
	v_cndmask_b32_e32 v56, v57, v56, vcc
	v_div_scale_f32 v57, s[0:1], v56, v56, 1.0
	v_rcp_f32_e32 v138, v57
	s_nop 0
	v_fma_f32 v139, -v57, v138, 1.0
	v_fmac_f32_e32 v138, v139, v138
	v_div_scale_f32 v139, vcc, 1.0, v56, 1.0
	v_mul_f32_e32 v140, v139, v138
	v_fma_f32 v141, -v57, v140, v139
	v_fmac_f32_e32 v140, v141, v138
	v_fma_f32 v57, -v57, v140, v139
	v_div_fmas_f32 v57, v57, v138, v140
	v_div_fixup_f32 v57, v57, v56, 1.0
	v_div_scale_f32 v56, s[0:1], v58, v58, 1.0
	v_rcp_f32_e32 v138, v56
	s_nop 0
	v_fma_f32 v139, -v56, v138, 1.0
	v_fmac_f32_e32 v138, v139, v138
	v_div_scale_f32 v139, vcc, 1.0, v58, 1.0
	v_mul_f32_e32 v140, v139, v138
	v_fma_f32 v141, -v56, v140, v139
	v_fmac_f32_e32 v140, v141, v138
	v_fma_f32 v56, -v56, v140, v139
	v_div_fmas_f32 v56, v56, v138, v140
	v_div_fixup_f32 v56, v56, v58, 1.0
	s_waitcnt vmcnt(2) lgkmcnt(0)
; __device__ __forceinline__ float row_rstd(const float* ssq, int row, int fq) {
;     const f32x4* p = (const f32x4*)(ssq + (size_t)row * 32 + fq * 8);
;     const f32x4 a = p[0], b = p[1];
;     float s = ((a[0] + a[1]) + (a[2] + a[3])) + ((b[0] + b[1]) + (b[2] + b[3]));
;     s += __shfl_xor(s, 16); s += __shfl_xor(s, 32);
;     return 1.0f / sqrtf(s * (1.0f / 2048.0f) + 1e-6f);
;     __device__ __forceinline__ void operator()(const f32x4 (&acc)[2][2][4][2], const Unit& u, int wr, int wc, int fr, int fq) const {
;     ...
;         if (u.pm != last_pm) { last_pm = u.pm;
; #pragma unroll
;             for (int ai = 0; ai < 2; ++ai)
; #pragma unroll
;                 for (int m = 0; m < 4; ++m) rs[ai][m] = row_rstd(ssq, row0 + ai * HALF + m * 16, fq); }
	v_mov_b32_e32 v138, v210
	v_mov_b32_e32 v139, v211
	v_mov_b32_e32 v140, v212
	v_mov_b32_e32 v141, v213
	v_mov_b32_e32 v142, v214
	v_mov_b32_e32 v143, v215
	v_mov_b32_e32 v144, v216
	v_mov_b32_e32 v145, v217
	v_mov_b32_e32 v166, v138
	v_mov_b32_e32 v167, v142
	v_mov_b32_e32 v142, v139
	v_pk_add_f32 v[138:139], v[166:167], v[142:143]
	v_mov_b32_e32 v142, v140
	v_mov_b32_e32 v143, v144
	v_mov_b32_e32 v144, v141
	v_pk_add_f32 v[140:141], v[142:143], v[144:145]
	s_nop 0
	v_pk_add_f32 v[138:139], v[138:139], v[140:141]
	s_nop 0
	v_add_f32_e32 v138, v138, v139
	ds_bpermute_b32 v139, v128, v138
	s_waitcnt lgkmcnt(0)
	v_add_f32_e32 v138, v138, v139
	ds_bpermute_b32 v139, v59, v138
	s_waitcnt lgkmcnt(0)
	v_add_f32_e32 v138, v138, v139
	v_fmamk_f32 v138, v138, 0x3a000000, v234
	v_cmp_gt_f32_e32 vcc, s33, v138
	v_mul_f32_e32 v139, 0x4f800000, v138
	s_nop 0
	v_cndmask_b32_e32 v138, v138, v139, vcc
	v_sqrt_f32_e32 v139, v138
	s_nop 0
	v_add_u32_e32 v140, -1, v139
	v_fma_f32 v141, -v140, v139, v138
	v_cmp_ge_f32_e64 s[8:9], 0, v141
	v_add_u32_e32 v141, 1, v139
	s_nop 0
	v_cndmask_b32_e64 v140, v139, v140, s[8:9]
	v_fma_f32 v139, -v141, v139, v138
	v_cmp_lt_f32_e64 s[8:9], 0, v139
	s_nop 1
	v_cndmask_b32_e64 v139, v140, v141, s[8:9]
	v_mul_f32_e32 v140, 0x37800000, v139
	v_cndmask_b32_e32 v139, v139, v140, vcc
	v_cmp_class_f32_e32 vcc, v138, v235
	s_nop 1
	v_cndmask_b32_e32 v165, v139, v138, vcc
	s_waitcnt vmcnt(0) lgkmcnt(0)
	v_mov_b32_e32 v138, v218
	v_mov_b32_e32 v139, v219
	v_mov_b32_e32 v140, v220
	v_mov_b32_e32 v141, v221
	v_mov_b32_e32 v142, v222
	v_mov_b32_e32 v143, v223
	v_mov_b32_e32 v144, v224
	v_mov_b32_e32 v145, v225
	v_mov_b32_e32 v166, v138
	v_mov_b32_e32 v167, v142
	v_mov_b32_e32 v142, v139
	v_pk_add_f32 v[138:139], v[166:167], v[142:143]
	v_mov_b32_e32 v142, v140
	v_mov_b32_e32 v143, v144
	v_mov_b32_e32 v144, v141
	v_pk_add_f32 v[140:141], v[142:143], v[144:145]
	s_nop 0
	v_pk_add_f32 v[138:139], v[138:139], v[140:141]
	s_nop 0
	v_add_f32_e32 v138, v138, v139
	ds_bpermute_b32 v139, v128, v138
	s_waitcnt lgkmcnt(0)
	v_add_f32_e32 v138, v138, v139
	ds_bpermute_b32 v139, v59, v138
	s_waitcnt lgkmcnt(0)
	v_add_f32_e32 v138, v138, v139
	v_fmamk_f32 v138, v138, 0x3a000000, v234
	v_cmp_gt_f32_e32 vcc, s33, v138
	v_mul_f32_e32 v139, 0x4f800000, v138
	s_nop 0
	v_cndmask_b32_e32 v138, v138, v139, vcc
	v_sqrt_f32_e32 v139, v138
	s_nop 0
	v_add_u32_e32 v140, -1, v139
	v_fma_f32 v141, -v140, v139, v138
	v_cmp_ge_f32_e64 s[8:9], 0, v141
	v_add_u32_e32 v141, 1, v139
	s_nop 0
	v_cndmask_b32_e64 v140, v139, v140, s[8:9]
	v_fma_f32 v139, -v141, v139, v138
	v_cmp_lt_f32_e64 s[8:9], 0, v139
	s_nop 1
	v_cndmask_b32_e64 v139, v140, v141, s[8:9]
	v_mul_f32_e32 v140, 0x37800000, v139
	v_cndmask_b32_e32 v139, v139, v140, vcc
	v_cmp_class_f32_e32 vcc, v138, v235
	s_nop 1
	v_cndmask_b32_e32 v138, v139, v138, vcc
	v_div_scale_f32 v139, s[0:1], v138, v138, 1.0
	v_rcp_f32_e32 v140, v139
	s_nop 0
	v_fma_f32 v141, -v139, v140, 1.0
	v_fmac_f32_e32 v140, v141, v140
	v_div_scale_f32 v141, vcc, 1.0, v138, 1.0
	v_mul_f32_e32 v142, v141, v140
	v_fma_f32 v143, -v139, v142, v141
	v_fmac_f32_e32 v142, v143, v140
	v_fma_f32 v139, -v139, v142, v141
	v_div_fmas_f32 v139, v139, v140, v142
	v_div_fixup_f32 v167, v139, v138, 1.0
	v_div_scale_f32 v138, s[0:1], v165, v165, 1.0
	v_rcp_f32_e32 v139, v138
	s_nop 0
	v_fma_f32 v140, -v138, v139, 1.0
	v_fmac_f32_e32 v139, v140, v139
	v_div_scale_f32 v140, vcc, 1.0, v165, 1.0
	v_mul_f32_e32 v141, v140, v139
	v_fma_f32 v142, -v138, v141, v140
	v_fmac_f32_e32 v141, v142, v139
	v_fma_f32 v138, -v138, v141, v140
	v_div_fmas_f32 v138, v138, v139, v141
	v_div_fixup_f32 v166, v138, v165, 1.0
	v_mov_b32_e32 v226, v178
	v_mov_b32_e32 v227, 0
	v_lshlrev_b64 v[226:227], 7, v[226:227]
	v_lshl_add_u64 v[226:227], v[154:155], 0, v[226:227]
	global_load_dwordx4 v[194:197], v[226:227], off
	global_load_dwordx4 v[198:201], v[226:227], off offset:16
	v_mov_b32_e32 v226, v176
	v_mov_b32_e32 v227, 0
	v_lshlrev_b64 v[226:227], 7, v[226:227]
	v_lshl_add_u64 v[226:227], v[154:155], 0, v[226:227]
	global_load_dwordx4 v[202:205], v[226:227], off
	global_load_dwordx4 v[206:209], v[226:227], off offset:16
	v_mov_b32_e32 v226, v168
	v_mov_b32_e32 v227, 0
	v_lshlrev_b64 v[226:227], 7, v[226:227]
	v_lshl_add_u64 v[226:227], v[154:155], 0, v[226:227]
	global_load_dwordx4 v[210:213], v[226:227], off
	global_load_dwordx4 v[214:217], v[226:227], off offset:16
	v_mov_b32_e32 v226, v164
	v_mov_b32_e32 v227, 0
	v_lshlrev_b64 v[226:227], 7, v[226:227]
	v_lshl_add_u64 v[226:227], v[154:155], 0, v[226:227]
	global_load_dwordx4 v[218:221], v[226:227], off
	global_load_dwordx4 v[222:225], v[226:227], off offset:16
	s_waitcnt vmcnt(6) lgkmcnt(0)
	v_mov_b32_e32 v138, v194
	v_mov_b32_e32 v139, v195
	v_mov_b32_e32 v140, v196
	v_mov_b32_e32 v141, v197
	v_mov_b32_e32 v142, v198
	v_mov_b32_e32 v143, v199
	v_mov_b32_e32 v144, v200
	v_mov_b32_e32 v145, v201
	v_mov_b32_e32 v182, v138
	v_mov_b32_e32 v183, v142
	v_mov_b32_e32 v142, v139
	v_pk_add_f32 v[138:139], v[182:183], v[142:143]
	v_mov_b32_e32 v142, v140
	v_mov_b32_e32 v143, v144
	v_mov_b32_e32 v144, v141
	v_pk_add_f32 v[140:141], v[142:143], v[144:145]
	s_nop 0
	v_pk_add_f32 v[138:139], v[138:139], v[140:141]
	s_nop 0
	v_add_f32_e32 v138, v138, v139
	ds_bpermute_b32 v139, v128, v138
	s_waitcnt lgkmcnt(0)
	v_add_f32_e32 v138, v138, v139
	ds_bpermute_b32 v139, v59, v138
	s_waitcnt lgkmcnt(0)
; __device__ __forceinline__ float row_rstd(const float* ssq, int row, int fq) {
;     const f32x4* p = (const f32x4*)(ssq + (size_t)row * 32 + fq * 8);
;     const f32x4 a = p[0], b = p[1];
;     float s = ((a[0] + a[1]) + (a[2] + a[3])) + ((b[0] + b[1]) + (b[2] + b[3]));
;     s += __shfl_xor(s, 16); s += __shfl_xor(s, 32);
;     return 1.0f / sqrtf(s * (1.0f / 2048.0f) + 1e-6f);
;     __device__ __forceinline__ void operator()(const f32x4 (&acc)[2][2][4][2], const Unit& u, int wr, int wc, int fr, int fq) const {
;     ...
;         if (u.pm != last_pm) { last_pm = u.pm;
; #pragma unroll
;             for (int ai = 0; ai < 2; ++ai)
; #pragma unroll
;                 for (int m = 0; m < 4; ++m) rs[ai][m] = row_rstd(ssq, row0 + ai * HALF + m * 16, fq); }
	v_add_f32_e32 v138, v138, v139
	v_fmamk_f32 v138, v138, 0x3a000000, v234
	v_cmp_gt_f32_e32 vcc, s33, v138
	v_mul_f32_e32 v139, 0x4f800000, v138
	s_nop 0
	v_cndmask_b32_e32 v138, v138, v139, vcc
	v_sqrt_f32_e32 v139, v138
	s_nop 0
	v_add_u32_e32 v140, -1, v139
	v_fma_f32 v141, -v140, v139, v138
	v_cmp_ge_f32_e64 s[8:9], 0, v141
	v_add_u32_e32 v141, 1, v139
	s_nop 0
	v_cndmask_b32_e64 v140, v139, v140, s[8:9]
	v_fma_f32 v139, -v141, v139, v138
	v_cmp_lt_f32_e64 s[8:9], 0, v139
	s_nop 1
	v_cndmask_b32_e64 v139, v140, v141, s[8:9]
	v_mul_f32_e32 v140, 0x37800000, v139
	v_cndmask_b32_e32 v139, v139, v140, vcc
	v_cmp_class_f32_e32 vcc, v138, v235
	s_nop 1
	v_cndmask_b32_e32 v165, v139, v138, vcc
	s_waitcnt vmcnt(4) lgkmcnt(0)
	v_mov_b32_e32 v138, v202
	v_mov_b32_e32 v139, v203
	v_mov_b32_e32 v140, v204
	v_mov_b32_e32 v141, v205
	v_mov_b32_e32 v142, v206
	v_mov_b32_e32 v143, v207
	v_mov_b32_e32 v144, v208
	v_mov_b32_e32 v145, v209
	v_mov_b32_e32 v182, v138
	v_mov_b32_e32 v183, v142
	v_mov_b32_e32 v142, v139
	v_pk_add_f32 v[138:139], v[182:183], v[142:143]
	v_mov_b32_e32 v142, v140
	v_mov_b32_e32 v143, v144
	v_mov_b32_e32 v144, v141
	v_pk_add_f32 v[140:141], v[142:143], v[144:145]
	s_nop 0
	v_pk_add_f32 v[138:139], v[138:139], v[140:141]
	s_nop 0
	v_add_f32_e32 v138, v138, v139
	ds_bpermute_b32 v139, v128, v138
	s_waitcnt lgkmcnt(0)
	v_add_f32_e32 v138, v138, v139
	ds_bpermute_b32 v139, v59, v138
	s_waitcnt lgkmcnt(0)
	v_add_f32_e32 v138, v138, v139
	v_fmamk_f32 v138, v138, 0x3a000000, v234
	v_cmp_gt_f32_e32 vcc, s33, v138
	v_mul_f32_e32 v139, 0x4f800000, v138
	s_nop 0
	v_cndmask_b32_e32 v138, v138, v139, vcc
	v_sqrt_f32_e32 v139, v138
	s_nop 0
	v_add_u32_e32 v140, -1, v139
	v_fma_f32 v141, -v140, v139, v138
	v_cmp_ge_f32_e64 s[8:9], 0, v141
	v_add_u32_e32 v141, 1, v139
	s_nop 0
	v_cndmask_b32_e64 v140, v139, v140, s[8:9]
	v_fma_f32 v139, -v141, v139, v138
	v_cmp_lt_f32_e64 s[8:9], 0, v139
	s_nop 1
	v_cndmask_b32_e64 v139, v140, v141, s[8:9]
	v_mul_f32_e32 v140, 0x37800000, v139
	v_cndmask_b32_e32 v139, v139, v140, vcc
	v_cmp_class_f32_e32 vcc, v138, v235
	s_nop 1
	v_cndmask_b32_e32 v138, v139, v138, vcc
	v_div_scale_f32 v139, s[0:1], v138, v138, 1.0
	v_rcp_f32_e32 v140, v139
	s_nop 0
	v_fma_f32 v141, -v139, v140, 1.0
	v_fmac_f32_e32 v140, v141, v140
	v_div_scale_f32 v141, vcc, 1.0, v138, 1.0
	v_mul_f32_e32 v142, v141, v140
	v_fma_f32 v143, -v139, v142, v141
	v_fmac_f32_e32 v142, v143, v140
	v_fma_f32 v139, -v139, v142, v141
	v_div_fmas_f32 v139, v139, v140, v142
	v_div_fixup_f32 v183, v139, v138, 1.0
	v_div_scale_f32 v138, s[0:1], v165, v165, 1.0
	v_rcp_f32_e32 v139, v138
	s_nop 0
	v_fma_f32 v140, -v138, v139, 1.0
	v_fmac_f32_e32 v139, v140, v139
	v_div_scale_f32 v140, vcc, 1.0, v165, 1.0
	v_mul_f32_e32 v141, v140, v139
	v_fma_f32 v142, -v138, v141, v140
	v_fmac_f32_e32 v141, v142, v139
	v_fma_f32 v138, -v138, v141, v140
	v_div_fmas_f32 v138, v138, v139, v141
	v_div_fixup_f32 v182, v138, v165, 1.0
	v_ashrrev_i32_e32 v165, 31, v164
	s_waitcnt vmcnt(2) lgkmcnt(0)
	v_mov_b32_e32 v138, v210
	v_mov_b32_e32 v139, v211
	v_mov_b32_e32 v140, v212
	v_mov_b32_e32 v141, v213
	v_mov_b32_e32 v142, v214
	v_mov_b32_e32 v143, v215
	v_mov_b32_e32 v144, v216
	v_mov_b32_e32 v145, v217
	v_mov_b32_e32 v190, v138
	v_mov_b32_e32 v191, v142
	v_mov_b32_e32 v142, v139
	v_pk_add_f32 v[138:139], v[190:191], v[142:143]
	v_mov_b32_e32 v142, v140
	v_mov_b32_e32 v143, v144
	v_mov_b32_e32 v144, v141
	v_pk_add_f32 v[140:141], v[142:143], v[144:145]
	s_nop 0
	v_pk_add_f32 v[138:139], v[138:139], v[140:141]
	s_nop 0
	v_add_f32_e32 v138, v138, v139
	ds_bpermute_b32 v139, v128, v138
	s_waitcnt lgkmcnt(0)
	v_add_f32_e32 v138, v138, v139
	ds_bpermute_b32 v139, v59, v138
	s_waitcnt lgkmcnt(0)
	v_add_f32_e32 v138, v138, v139
	v_fmamk_f32 v138, v138, 0x3a000000, v234
	v_cmp_gt_f32_e32 vcc, s33, v138
	v_mul_f32_e32 v139, 0x4f800000, v138
	s_nop 0
	v_cndmask_b32_e32 v138, v138, v139, vcc
	v_sqrt_f32_e32 v139, v138
	s_nop 0
	v_add_u32_e32 v140, -1, v139
	v_fma_f32 v141, -v140, v139, v138
	v_cmp_ge_f32_e64 s[8:9], 0, v141
	v_add_u32_e32 v141, 1, v139
	s_nop 0
	v_cndmask_b32_e64 v140, v139, v140, s[8:9]
	v_fma_f32 v139, -v141, v139, v138
	v_cmp_lt_f32_e64 s[8:9], 0, v139
	s_nop 1
	v_cndmask_b32_e64 v139, v140, v141, s[8:9]
	v_mul_f32_e32 v140, 0x37800000, v139
	v_cndmask_b32_e32 v139, v139, v140, vcc
	v_cmp_class_f32_e32 vcc, v138, v235
	s_nop 1
	v_cndmask_b32_e32 v190, v139, v138, vcc
	s_waitcnt vmcnt(0) lgkmcnt(0)
	v_mov_b32_e32 v142, v218
	v_mov_b32_e32 v143, v219
	v_mov_b32_e32 v144, v220
	v_mov_b32_e32 v145, v221
	v_mov_b32_e32 v138, v222
	v_mov_b32_e32 v139, v223
	v_mov_b32_e32 v140, v224
	v_mov_b32_e32 v141, v225
	v_mov_b32_e32 v192, v142
	v_mov_b32_e32 v193, v138
	v_mov_b32_e32 v138, v143
	v_mov_b32_e32 v142, v144
	v_mov_b32_e32 v143, v140
	v_mov_b32_e32 v140, v145
	v_pk_add_f32 v[138:139], v[192:193], v[138:139]
	v_pk_add_f32 v[140:141], v[142:143], v[140:141]
	s_nop 0
	v_pk_add_f32 v[138:139], v[138:139], v[140:141]
	s_nop 0
	v_add_f32_e32 v138, v138, v139
	ds_bpermute_b32 v128, v128, v138
	s_waitcnt lgkmcnt(0)
	v_add_f32_e32 v128, v138, v128
	ds_bpermute_b32 v59, v59, v128
	s_waitcnt lgkmcnt(0)
	v_add_f32_e32 v59, v128, v59
	v_fmamk_f32 v59, v59, 0x3a000000, v234
	v_cmp_gt_f32_e32 vcc, s33, v59
	v_mul_f32_e32 v128, 0x4f800000, v59
	s_nop 0
	v_cndmask_b32_e32 v59, v59, v128, vcc
	v_sqrt_f32_e32 v128, v59
	s_nop 0
	v_add_u32_e32 v138, -1, v128
	v_fma_f32 v139, -v138, v128, v59
	v_cmp_ge_f32_e64 s[8:9], 0, v139
	v_add_u32_e32 v139, 1, v128
	s_nop 0
	v_cndmask_b32_e64 v138, v128, v138, s[8:9]
	v_fma_f32 v128, -v139, v128, v59
	v_cmp_lt_f32_e64 s[8:9], 0, v128
	s_nop 1
	v_cndmask_b32_e64 v128, v138, v139, s[8:9]
	v_mul_f32_e32 v138, 0x37800000, v128
	v_cndmask_b32_e32 v128, v128, v138, vcc
	v_cmp_class_f32_e32 vcc, v59, v235
	s_nop 1
	v_cndmask_b32_e32 v59, v128, v59, vcc
	v_div_scale_f32 v128, s[0:1], v59, v59, 1.0
	v_rcp_f32_e32 v138, v128
	s_nop 0
	v_fma_f32 v139, -v128, v138, 1.0
	v_fmac_f32_e32 v138, v139, v138
	v_div_scale_f32 v139, vcc, 1.0, v59, 1.0
	v_mul_f32_e32 v140, v139, v138
	v_fma_f32 v141, -v128, v140, v139
	v_fmac_f32_e32 v140, v141, v138
	v_fma_f32 v128, -v128, v140, v139
	v_div_fmas_f32 v128, v128, v138, v140
	v_div_fixup_f32 v139, v128, v59, 1.0
	v_div_scale_f32 v59, s[0:1], v190, v190, 1.0
	v_rcp_f32_e32 v128, v59
	s_mov_b64 s[0:1], 0
	v_fma_f32 v138, -v59, v128, 1.0
	v_fmac_f32_e32 v128, v138, v128
	v_div_scale_f32 v138, vcc, 1.0, v190, 1.0
	v_mul_f32_e32 v140, v138, v128
	v_fma_f32 v141, -v59, v140, v138
	v_fmac_f32_e32 v140, v141, v128
	v_fma_f32 v59, -v59, v140, v138
	v_div_fmas_f32 v59, v59, v128, v140
	v_div_fixup_f32 v138, v59, v190, 1.0
